# conv module LayerNorm+SiLU stage: the 16 norm weight/bias loads (4 serialized groups) issued once before the stage barrier into fresh registers, single wait
# speedup vs baseline: 1.0012x; 1.0012x over previous
.LBB0_818:
	s_or_b64 exec, exec, s[0:1]
	s_waitcnt vmcnt(9)
	v_ashrrev_i32_e32 v35, 8, v50
	s_waitcnt vmcnt(1)
	v_lshlrev_b32_e32 v0, 14, v35
	v_lshlrev_b32_sdwa v1, v236, v50 dst_sel:DWORD dst_unused:UNUSED_PAD src0_sel:DWORD src1_sel:BYTE_0
	v_add3_u32 v34, 0, v0, v1
	s_waitcnt lgkmcnt(0)
	s_barrier
	ds_read_u16 v0, v34
	ds_read_u16 v1, v34 offset:16384
	ds_read_u16 v2, v34 offset:16896
	v_lshlrev_b32_e32 v35, 15, v35
	v_lshlrev_b32_sdwa v87, v246, v50 dst_sel:DWORD dst_unused:UNUSED_PAD src0_sel:DWORD src1_sel:BYTE_0
	s_waitcnt lgkmcnt(2)
	v_lshlrev_b32_e32 v97, 16, v0
	ds_read_u16 v0, v34 offset:512
	ds_read_u16 v3, v34 offset:17408
	v_fma_f32 v97, v53, v97, v86
	s_waitcnt lgkmcnt(3)
	v_lshlrev_b32_e32 v1, 16, v1
	s_waitcnt lgkmcnt(2)
	v_lshlrev_b32_e32 v2, 16, v2
	s_waitcnt lgkmcnt(1)
	v_lshlrev_b32_e32 v96, 16, v0
	ds_read_u16 v0, v34 offset:1024
	s_waitcnt vmcnt(0)
	ds_read_u16 v4, v34 offset:17920
	v_fmac_f32_e32 v97, v54, v96
	v_fma_f32 v96, v53, v96, v86
	ds_read_u16 v5, v34 offset:18432
	s_waitcnt lgkmcnt(2)
	v_lshlrev_b32_e32 v95, 16, v0
	ds_read_u16 v0, v34 offset:1536
	v_fmac_f32_e32 v97, v55, v95
	v_fmac_f32_e32 v96, v54, v95
	ds_read_u16 v6, v34 offset:18944
	v_fma_f32 v95, v53, v95, v86
	s_waitcnt lgkmcnt(1)
	v_lshlrev_b32_e32 v94, 16, v0
	ds_read_u16 v0, v34 offset:2048
	v_fmac_f32_e32 v97, v56, v94
	ds_read_u16 v7, v34 offset:19456
	v_fmac_f32_e32 v96, v55, v94
	v_fmac_f32_e32 v95, v54, v94
	s_waitcnt lgkmcnt(1)
	v_lshlrev_b32_e32 v93, 16, v0
	ds_read_u16 v0, v34 offset:2560
	ds_read_u16 v9, v34 offset:19968
	v_fma_f32 v94, v53, v94, v86
	v_fmac_f32_e32 v97, v57, v93
	v_fmac_f32_e32 v96, v56, v93
	s_waitcnt lgkmcnt(1)
	v_lshlrev_b32_e32 v92, 16, v0
	ds_read_u16 v0, v34 offset:3072
	ds_read_u16 v10, v34 offset:20480
	v_fmac_f32_e32 v95, v55, v93
	v_fmac_f32_e32 v94, v54, v93
	v_fma_f32 v93, v53, v93, v86
	s_waitcnt lgkmcnt(1)
	v_lshlrev_b32_e32 v91, 16, v0
	ds_read_u16 v0, v34 offset:3584
	ds_read_u16 v11, v34 offset:20992
	v_fmac_f32_e32 v97, v58, v92
	v_fmac_f32_e32 v96, v57, v92
	ds_read_u16 v12, v34 offset:21504
	s_waitcnt lgkmcnt(2)
	v_lshlrev_b32_e32 v90, 16, v0
	ds_read_u16 v0, v34 offset:4096
	v_fmac_f32_e32 v95, v56, v92
	v_fmac_f32_e32 v94, v55, v92
	ds_read_u16 v13, v34 offset:22016
	v_fmac_f32_e32 v93, v54, v92
	s_waitcnt lgkmcnt(1)
	v_lshlrev_b32_e32 v89, 16, v0
	ds_read_u16 v0, v34 offset:4608
	v_fma_f32 v92, v53, v92, v86
	ds_read_u16 v14, v34 offset:22528
	v_fmac_f32_e32 v97, v59, v91
	v_fmac_f32_e32 v96, v58, v91
	s_waitcnt lgkmcnt(1)
	v_lshlrev_b32_e32 v88, 16, v0
	ds_read_u16 v0, v34 offset:5120
	ds_read_u16 v15, v34 offset:23040
	v_fmac_f32_e32 v95, v57, v91
	v_fmac_f32_e32 v94, v56, v91
	v_fmac_f32_e32 v93, v55, v91
	s_waitcnt lgkmcnt(1)
	v_lshlrev_b32_e32 v64, 16, v0
	ds_read_u16 v0, v34 offset:5632
	ds_read_u16 v16, v34 offset:23552
	v_fmac_f32_e32 v92, v54, v91
	v_fma_f32 v91, v53, v91, v86
	v_fmac_f32_e32 v97, v60, v90
	s_waitcnt lgkmcnt(1)
	v_lshlrev_b32_e32 v52, 16, v0
	ds_read_u16 v0, v34 offset:6144
	ds_read_u16 v18, v34 offset:24064
	v_fmac_f32_e32 v96, v59, v90
	v_fmac_f32_e32 v95, v58, v90
	ds_read_u16 v19, v34 offset:24576
	s_waitcnt lgkmcnt(2)
	v_lshlrev_b32_e32 v51, 16, v0
	ds_read_u16 v0, v34 offset:6656
	v_fmac_f32_e32 v94, v57, v90
	v_fmac_f32_e32 v93, v56, v90
	ds_read_u16 v20, v34 offset:25088
	v_fmac_f32_e32 v92, v55, v90
	s_waitcnt lgkmcnt(1)
	v_lshlrev_b32_e32 v49, 16, v0
	ds_read_u16 v0, v34 offset:7168
	v_fmac_f32_e32 v91, v54, v90
	ds_read_u16 v21, v34 offset:25600
	v_fma_f32 v90, v53, v90, v86
	v_fmac_f32_e32 v97, v61, v89
	s_waitcnt lgkmcnt(1)
	v_lshlrev_b32_e32 v48, 16, v0
	ds_read_u16 v0, v34 offset:7680
	ds_read_u16 v22, v34 offset:26112
	v_fmac_f32_e32 v96, v60, v89
	v_fmac_f32_e32 v95, v59, v89
	v_fmac_f32_e32 v94, v58, v89
	s_waitcnt lgkmcnt(1)
	v_lshlrev_b32_e32 v47, 16, v0
	ds_read_u16 v0, v34 offset:8192
	ds_read_u16 v23, v34 offset:26624
	v_fmac_f32_e32 v93, v57, v89
	v_fmac_f32_e32 v92, v56, v89
	v_fmac_f32_e32 v91, v55, v89
	s_waitcnt lgkmcnt(1)
	v_lshlrev_b32_e32 v46, 16, v0
	ds_read_u16 v0, v34 offset:8704
	ds_read_u16 v24, v34 offset:27136
	v_fmac_f32_e32 v90, v54, v89
	v_fma_f32 v89, v53, v89, v86
	ds_read_u16 v25, v34 offset:27648
	s_waitcnt lgkmcnt(2)
	v_lshlrev_b32_e32 v45, 16, v0
	ds_read_u16 v0, v34 offset:9216
	v_fmac_f32_e32 v97, v62, v88
	v_fmac_f32_e32 v96, v61, v88
	ds_read_u16 v27, v34 offset:28160
	v_fmac_f32_e32 v95, v60, v88
	s_waitcnt lgkmcnt(1)
	v_lshlrev_b32_e32 v44, 16, v0
	ds_read_u16 v0, v34 offset:9728
	v_fmac_f32_e32 v94, v59, v88
	ds_read_u16 v28, v34 offset:28672
	v_fmac_f32_e32 v93, v58, v88
	v_fmac_f32_e32 v92, v57, v88
	s_waitcnt lgkmcnt(1)
	v_lshlrev_b32_e32 v43, 16, v0
	ds_read_u16 v0, v34 offset:10240
	ds_read_u16 v29, v34 offset:29184
	v_fmac_f32_e32 v91, v56, v88
	v_fmac_f32_e32 v90, v55, v88
	v_fmac_f32_e32 v89, v54, v88
	s_waitcnt lgkmcnt(1)
	v_lshlrev_b32_e32 v42, 16, v0
	ds_read_u16 v0, v34 offset:10752
	ds_read_u16 v30, v34 offset:29696
	v_fma_f32 v88, v53, v88, v86
	v_fmac_f32_e32 v97, v63, v64
	v_fmac_f32_e32 v96, v62, v64
	s_waitcnt lgkmcnt(1)
	v_lshlrev_b32_e32 v41, 16, v0
	ds_read_u16 v0, v34 offset:11264
	ds_read_u16 v31, v34 offset:30208
	v_fmac_f32_e32 v95, v61, v64
	v_fmac_f32_e32 v94, v60, v64
	v_fmac_f32_e32 v93, v59, v64
	s_waitcnt lgkmcnt(1)
	v_lshlrev_b32_e32 v40, 16, v0
	ds_read_u16 v0, v34 offset:11776
	v_fmac_f32_e32 v92, v58, v64
	v_fmac_f32_e32 v91, v57, v64
	v_fmac_f32_e32 v90, v56, v64
	v_fmac_f32_e32 v89, v55, v64
	s_waitcnt lgkmcnt(0)
	v_lshlrev_b32_e32 v39, 16, v0
	ds_read_u16 v0, v34 offset:12288
	v_fmac_f32_e32 v88, v54, v64
	v_fma_f32 v64, v53, v64, v86
	v_fmac_f32_e32 v97, v66, v52
	v_fmac_f32_e32 v96, v63, v52
	s_waitcnt lgkmcnt(0)
	v_lshlrev_b32_e32 v38, 16, v0
	ds_read_u16 v0, v34 offset:12800
	v_fmac_f32_e32 v95, v62, v52
	v_fmac_f32_e32 v94, v61, v52
	v_fmac_f32_e32 v93, v60, v52
	v_fmac_f32_e32 v92, v59, v52
	s_waitcnt lgkmcnt(0)
	v_lshlrev_b32_e32 v37, 16, v0
	ds_read_u16 v0, v34 offset:13312
	v_fmac_f32_e32 v91, v58, v52
	v_fmac_f32_e32 v90, v57, v52
	v_fmac_f32_e32 v89, v56, v52
	v_fmac_f32_e32 v88, v55, v52
	s_waitcnt lgkmcnt(0)
	v_lshlrev_b32_e32 v36, 16, v0
	ds_read_u16 v0, v34 offset:13824
	v_fmac_f32_e32 v64, v54, v52
	v_fma_f32 v52, v53, v52, v86
	v_fmac_f32_e32 v97, v67, v51
	v_fmac_f32_e32 v96, v66, v51
	s_waitcnt lgkmcnt(0)
	v_lshlrev_b32_e32 v33, 16, v0
	ds_read_u16 v0, v34 offset:14336
	ds_read_u16 v32, v34 offset:30720
	v_fmac_f32_e32 v95, v63, v51
	v_fmac_f32_e32 v94, v62, v51
	v_fmac_f32_e32 v93, v61, v51
	v_fmac_f32_e32 v92, v60, v51
	v_fmac_f32_e32 v91, v59, v51
	v_fmac_f32_e32 v90, v58, v51
	v_fmac_f32_e32 v89, v57, v51
	v_fmac_f32_e32 v88, v56, v51
	v_fmac_f32_e32 v64, v55, v51
	v_fmac_f32_e32 v52, v54, v51
	v_fma_f32 v51, v53, v51, v86
	v_fmac_f32_e32 v97, v68, v49
	v_fmac_f32_e32 v96, v67, v49
	v_fmac_f32_e32 v95, v66, v49
	v_fmac_f32_e32 v94, v63, v49
	v_fmac_f32_e32 v93, v62, v49
	v_fmac_f32_e32 v92, v61, v49
	v_fmac_f32_e32 v91, v60, v49
	v_fmac_f32_e32 v90, v59, v49
	v_fmac_f32_e32 v89, v58, v49
	v_fmac_f32_e32 v88, v57, v49
	v_fmac_f32_e32 v64, v56, v49
	v_fmac_f32_e32 v52, v55, v49
	v_fmac_f32_e32 v51, v54, v49
	v_fma_f32 v49, v53, v49, v86
	v_fmac_f32_e32 v97, v69, v48
	v_fmac_f32_e32 v96, v68, v48
	v_fmac_f32_e32 v95, v67, v48
	v_fmac_f32_e32 v94, v66, v48
	v_fmac_f32_e32 v93, v63, v48
	v_fmac_f32_e32 v92, v62, v48
	v_fmac_f32_e32 v91, v61, v48
	v_fmac_f32_e32 v90, v60, v48
	v_fmac_f32_e32 v89, v59, v48
	v_fmac_f32_e32 v88, v58, v48
	v_fmac_f32_e32 v64, v57, v48
	v_fmac_f32_e32 v52, v56, v48
	v_fmac_f32_e32 v51, v55, v48
	v_fmac_f32_e32 v49, v54, v48
	v_fma_f32 v48, v53, v48, v86
	s_waitcnt lgkmcnt(1)
	v_lshlrev_b32_e32 v26, 16, v0
	ds_read_u16 v0, v34 offset:14848
	v_fmac_f32_e32 v97, v70, v47
	v_fmac_f32_e32 v96, v69, v47
	v_fmac_f32_e32 v95, v68, v47
	v_fmac_f32_e32 v94, v67, v47
	v_fmac_f32_e32 v93, v66, v47
	v_fmac_f32_e32 v92, v63, v47
	v_fmac_f32_e32 v91, v62, v47
	v_fmac_f32_e32 v90, v61, v47
	v_fmac_f32_e32 v89, v60, v47
	v_fmac_f32_e32 v88, v59, v47
	v_fmac_f32_e32 v64, v58, v47
	v_fmac_f32_e32 v52, v57, v47
	v_fmac_f32_e32 v51, v56, v47
	v_fmac_f32_e32 v49, v55, v47
	v_fmac_f32_e32 v48, v54, v47
	v_fma_f32 v47, v53, v47, v86
	v_fmac_f32_e32 v97, v71, v46
	v_fmac_f32_e32 v96, v70, v46
	v_fmac_f32_e32 v95, v69, v46
	v_fmac_f32_e32 v94, v68, v46
	v_fmac_f32_e32 v93, v67, v46
	v_fmac_f32_e32 v92, v66, v46
	v_fmac_f32_e32 v91, v63, v46
	v_fmac_f32_e32 v90, v62, v46
	v_fmac_f32_e32 v89, v61, v46
	v_fmac_f32_e32 v88, v60, v46
	v_fmac_f32_e32 v64, v59, v46
	v_fmac_f32_e32 v52, v58, v46
	v_fmac_f32_e32 v51, v57, v46
	v_fmac_f32_e32 v49, v56, v46
	v_fmac_f32_e32 v48, v55, v46
	v_fmac_f32_e32 v47, v54, v46
	v_fma_f32 v46, v53, v46, v86
	v_fmac_f32_e32 v97, v72, v45
	v_fmac_f32_e32 v96, v71, v45
	v_fmac_f32_e32 v95, v70, v45
	v_fmac_f32_e32 v94, v69, v45
	v_fmac_f32_e32 v93, v68, v45
	v_fmac_f32_e32 v92, v67, v45
	v_fmac_f32_e32 v91, v66, v45
	v_fmac_f32_e32 v90, v63, v45
	v_fmac_f32_e32 v89, v62, v45
	v_fmac_f32_e32 v88, v61, v45
	v_fmac_f32_e32 v64, v60, v45
	v_fmac_f32_e32 v52, v59, v45
	v_fmac_f32_e32 v51, v58, v45
	v_fmac_f32_e32 v49, v57, v45
	v_fmac_f32_e32 v48, v56, v45
	v_fmac_f32_e32 v47, v55, v45
	v_fmac_f32_e32 v46, v54, v45
	v_fma_f32 v45, v53, v45, v86
	v_fmac_f32_e32 v97, v73, v44
	v_fmac_f32_e32 v96, v72, v44
	v_fmac_f32_e32 v95, v71, v44
	v_fmac_f32_e32 v94, v70, v44
	v_fmac_f32_e32 v93, v69, v44
	v_fmac_f32_e32 v92, v68, v44
	v_fmac_f32_e32 v91, v67, v44
	v_fmac_f32_e32 v90, v66, v44
	v_fmac_f32_e32 v89, v63, v44
	v_fmac_f32_e32 v88, v62, v44
	v_fmac_f32_e32 v64, v61, v44
	v_fmac_f32_e32 v52, v60, v44
	v_fmac_f32_e32 v51, v59, v44
	v_fmac_f32_e32 v49, v58, v44
	v_fmac_f32_e32 v48, v57, v44
	v_fmac_f32_e32 v47, v56, v44
	v_fmac_f32_e32 v46, v55, v44
	v_fmac_f32_e32 v45, v54, v44
	v_fma_f32 v44, v53, v44, v86
	v_fmac_f32_e32 v97, v74, v43
	v_fmac_f32_e32 v96, v73, v43
	v_fmac_f32_e32 v95, v72, v43
	v_fmac_f32_e32 v94, v71, v43
	v_fmac_f32_e32 v93, v70, v43
	v_fmac_f32_e32 v92, v69, v43
	v_fmac_f32_e32 v91, v68, v43
	v_fmac_f32_e32 v90, v67, v43
	v_fmac_f32_e32 v89, v66, v43
	v_fmac_f32_e32 v88, v63, v43
	v_fmac_f32_e32 v64, v62, v43
	v_fmac_f32_e32 v52, v61, v43
	v_fmac_f32_e32 v51, v60, v43
	v_fmac_f32_e32 v49, v59, v43
	v_fmac_f32_e32 v48, v58, v43
	v_fmac_f32_e32 v47, v57, v43
	v_fmac_f32_e32 v46, v56, v43
	v_fmac_f32_e32 v45, v55, v43
	v_fmac_f32_e32 v44, v54, v43
	v_fma_f32 v43, v53, v43, v86
	s_waitcnt lgkmcnt(0)
	v_lshlrev_b32_e32 v17, 16, v0
	ds_read_u16 v0, v34 offset:15360
	v_fmac_f32_e32 v97, v75, v42
	v_fmac_f32_e32 v96, v74, v42
	v_fmac_f32_e32 v95, v73, v42
	v_fmac_f32_e32 v94, v72, v42
	v_fmac_f32_e32 v93, v71, v42
	v_fmac_f32_e32 v92, v70, v42
	v_fmac_f32_e32 v91, v69, v42
	v_fmac_f32_e32 v90, v68, v42
	v_fmac_f32_e32 v89, v67, v42
	v_fmac_f32_e32 v88, v66, v42
	v_fmac_f32_e32 v64, v63, v42
	v_fmac_f32_e32 v52, v62, v42
	v_fmac_f32_e32 v51, v61, v42
	v_fmac_f32_e32 v49, v60, v42
	v_fmac_f32_e32 v48, v59, v42
	v_fmac_f32_e32 v47, v58, v42
	v_fmac_f32_e32 v46, v57, v42
	v_fmac_f32_e32 v45, v56, v42
	v_fmac_f32_e32 v44, v55, v42
	v_fmac_f32_e32 v43, v54, v42
	v_fma_f32 v42, v53, v42, v86
	v_fmac_f32_e32 v97, v76, v41
	v_fmac_f32_e32 v96, v75, v41
	v_fmac_f32_e32 v95, v74, v41
	v_fmac_f32_e32 v94, v73, v41
	v_fmac_f32_e32 v93, v72, v41
	v_fmac_f32_e32 v92, v71, v41
	v_fmac_f32_e32 v91, v70, v41
	v_fmac_f32_e32 v90, v69, v41
	v_fmac_f32_e32 v89, v68, v41
	v_fmac_f32_e32 v88, v67, v41
	v_fmac_f32_e32 v64, v66, v41
	v_fmac_f32_e32 v52, v63, v41
	v_fmac_f32_e32 v51, v62, v41
	v_fmac_f32_e32 v49, v61, v41
	v_fmac_f32_e32 v48, v60, v41
	v_fmac_f32_e32 v47, v59, v41
	v_fmac_f32_e32 v46, v58, v41
	v_fmac_f32_e32 v45, v57, v41
	v_fmac_f32_e32 v44, v56, v41
	v_fmac_f32_e32 v43, v55, v41
	v_fmac_f32_e32 v42, v54, v41
	v_fma_f32 v41, v53, v41, v86
	v_fmac_f32_e32 v97, v77, v40
	v_fmac_f32_e32 v96, v76, v40
	v_fmac_f32_e32 v95, v75, v40
	v_fmac_f32_e32 v94, v74, v40
	v_fmac_f32_e32 v93, v73, v40
	v_fmac_f32_e32 v92, v72, v40
	v_fmac_f32_e32 v91, v71, v40
	v_fmac_f32_e32 v90, v70, v40
	v_fmac_f32_e32 v89, v69, v40
	v_fmac_f32_e32 v88, v68, v40
	v_fmac_f32_e32 v64, v67, v40
	v_fmac_f32_e32 v52, v66, v40
	v_fmac_f32_e32 v51, v63, v40
	v_fmac_f32_e32 v49, v62, v40
	v_fmac_f32_e32 v48, v61, v40
	v_fmac_f32_e32 v47, v60, v40
	v_fmac_f32_e32 v46, v59, v40
	v_fmac_f32_e32 v45, v58, v40
	v_fmac_f32_e32 v44, v57, v40
	v_fmac_f32_e32 v43, v56, v40
	v_fmac_f32_e32 v42, v55, v40
	v_fmac_f32_e32 v41, v54, v40
	v_fma_f32 v40, v53, v40, v86
	v_fmac_f32_e32 v97, v78, v39
	v_fmac_f32_e32 v96, v77, v39
	v_fmac_f32_e32 v95, v76, v39
	v_fmac_f32_e32 v94, v75, v39
	v_fmac_f32_e32 v93, v74, v39
	v_fmac_f32_e32 v92, v73, v39
	v_fmac_f32_e32 v91, v72, v39
	v_fmac_f32_e32 v90, v71, v39
	v_fmac_f32_e32 v89, v70, v39
	v_fmac_f32_e32 v88, v69, v39
	v_fmac_f32_e32 v64, v68, v39
	v_fmac_f32_e32 v52, v67, v39
	v_fmac_f32_e32 v51, v66, v39
	v_fmac_f32_e32 v49, v63, v39
	v_fmac_f32_e32 v48, v62, v39
	v_fmac_f32_e32 v47, v61, v39
	v_fmac_f32_e32 v46, v60, v39
	v_fmac_f32_e32 v45, v59, v39
	v_fmac_f32_e32 v44, v58, v39
	v_fmac_f32_e32 v43, v57, v39
	v_fmac_f32_e32 v42, v56, v39
	v_fmac_f32_e32 v41, v55, v39
	v_fmac_f32_e32 v40, v54, v39
	v_fma_f32 v39, v53, v39, v86
	v_fmac_f32_e32 v97, v79, v38
	v_fmac_f32_e32 v96, v78, v38
	v_fmac_f32_e32 v95, v77, v38
	v_fmac_f32_e32 v94, v76, v38
	v_fmac_f32_e32 v93, v75, v38
	v_fmac_f32_e32 v92, v74, v38
	v_fmac_f32_e32 v91, v73, v38
	v_fmac_f32_e32 v90, v72, v38
	v_fmac_f32_e32 v89, v71, v38
	v_fmac_f32_e32 v88, v70, v38
	v_fmac_f32_e32 v64, v69, v38
	v_fmac_f32_e32 v52, v68, v38
	v_fmac_f32_e32 v51, v67, v38
	v_fmac_f32_e32 v49, v66, v38
	v_fmac_f32_e32 v48, v63, v38
	v_fmac_f32_e32 v47, v62, v38
	v_fmac_f32_e32 v46, v61, v38
	v_fmac_f32_e32 v45, v60, v38
	v_fmac_f32_e32 v44, v59, v38
	v_fmac_f32_e32 v43, v58, v38
	v_fmac_f32_e32 v42, v57, v38
	v_fmac_f32_e32 v41, v56, v38
	v_fmac_f32_e32 v40, v55, v38
	v_fmac_f32_e32 v39, v54, v38
	v_fma_f32 v38, v53, v38, v86
	s_waitcnt lgkmcnt(0)
	v_lshlrev_b32_e32 v8, 16, v0
	ds_read_u16 v0, v34 offset:15872
	v_fmac_f32_e32 v97, v80, v37
	v_fmac_f32_e32 v96, v79, v37
	v_fmac_f32_e32 v95, v78, v37
	v_fmac_f32_e32 v94, v77, v37
	v_fmac_f32_e32 v93, v76, v37
	v_fmac_f32_e32 v92, v75, v37
	v_fmac_f32_e32 v91, v74, v37
	v_fmac_f32_e32 v90, v73, v37
	v_fmac_f32_e32 v89, v72, v37
	v_fmac_f32_e32 v88, v71, v37
	v_fmac_f32_e32 v64, v70, v37
	v_fmac_f32_e32 v52, v69, v37
	v_fmac_f32_e32 v51, v68, v37
	v_fmac_f32_e32 v49, v67, v37
	v_fmac_f32_e32 v48, v66, v37
	v_fmac_f32_e32 v47, v63, v37
	v_fmac_f32_e32 v46, v62, v37
	v_fmac_f32_e32 v45, v61, v37
	v_fmac_f32_e32 v44, v60, v37
	v_fmac_f32_e32 v43, v59, v37
	v_fmac_f32_e32 v42, v58, v37
	v_fmac_f32_e32 v41, v57, v37
	v_fmac_f32_e32 v40, v56, v37
	v_fmac_f32_e32 v39, v55, v37
	v_fmac_f32_e32 v38, v54, v37
	v_fma_f32 v37, v53, v37, v86
	v_fmac_f32_e32 v97, v81, v36
	v_fmac_f32_e32 v96, v80, v36
	v_fmac_f32_e32 v95, v79, v36
	v_fmac_f32_e32 v94, v78, v36
	v_fmac_f32_e32 v93, v77, v36
	v_fmac_f32_e32 v92, v76, v36
	v_fmac_f32_e32 v91, v75, v36
	v_fmac_f32_e32 v90, v74, v36
	v_fmac_f32_e32 v89, v73, v36
	v_fmac_f32_e32 v88, v72, v36
	v_fmac_f32_e32 v64, v71, v36
	v_fmac_f32_e32 v52, v70, v36
	v_fmac_f32_e32 v51, v69, v36
	v_fmac_f32_e32 v49, v68, v36
	v_fmac_f32_e32 v48, v67, v36
	v_fmac_f32_e32 v47, v66, v36
	v_fmac_f32_e32 v46, v63, v36
	v_fmac_f32_e32 v45, v62, v36
	v_fmac_f32_e32 v44, v61, v36
	v_fmac_f32_e32 v43, v60, v36
	v_fmac_f32_e32 v42, v59, v36
	v_fmac_f32_e32 v41, v58, v36
	v_fmac_f32_e32 v40, v57, v36
	v_fmac_f32_e32 v39, v56, v36
	v_fmac_f32_e32 v38, v55, v36
	v_fmac_f32_e32 v37, v54, v36
	v_fma_f32 v36, v53, v36, v86
	v_fmac_f32_e32 v97, v82, v33
	v_fmac_f32_e32 v96, v81, v33
	v_fmac_f32_e32 v95, v80, v33
	v_fmac_f32_e32 v94, v79, v33
	v_fmac_f32_e32 v93, v78, v33
	v_fmac_f32_e32 v92, v77, v33
	v_fmac_f32_e32 v91, v76, v33
	v_fmac_f32_e32 v90, v75, v33
	v_fmac_f32_e32 v89, v74, v33
	v_fmac_f32_e32 v88, v73, v33
	v_fmac_f32_e32 v64, v72, v33
	v_fmac_f32_e32 v52, v71, v33
	v_fmac_f32_e32 v51, v70, v33
	v_fmac_f32_e32 v49, v69, v33
	v_fmac_f32_e32 v48, v68, v33
	v_fmac_f32_e32 v47, v67, v33
	v_fmac_f32_e32 v46, v66, v33
	v_fmac_f32_e32 v45, v63, v33
	v_fmac_f32_e32 v44, v62, v33
	v_fmac_f32_e32 v43, v61, v33
	v_fmac_f32_e32 v42, v60, v33
	v_fmac_f32_e32 v41, v59, v33
	v_fmac_f32_e32 v40, v58, v33
	v_fmac_f32_e32 v39, v57, v33
	v_fmac_f32_e32 v38, v56, v33
	v_fmac_f32_e32 v37, v55, v33
	v_fmac_f32_e32 v36, v54, v33
	v_fma_f32 v33, v53, v33, v86
	v_fmac_f32_e32 v97, v83, v26
	v_fmac_f32_e32 v96, v82, v26
	v_fmac_f32_e32 v95, v81, v26
	v_fmac_f32_e32 v94, v80, v26
	v_fmac_f32_e32 v93, v79, v26
	v_fmac_f32_e32 v92, v78, v26
	v_fmac_f32_e32 v91, v77, v26
	v_fmac_f32_e32 v90, v76, v26
	v_fmac_f32_e32 v89, v75, v26
	v_fmac_f32_e32 v88, v74, v26
	v_fmac_f32_e32 v64, v73, v26
	v_fmac_f32_e32 v52, v72, v26
	v_fmac_f32_e32 v51, v71, v26
	v_fmac_f32_e32 v49, v70, v26
	v_fmac_f32_e32 v48, v69, v26
	v_fmac_f32_e32 v47, v68, v26
	v_fmac_f32_e32 v46, v67, v26
	v_fmac_f32_e32 v45, v66, v26
	v_fmac_f32_e32 v44, v63, v26
	v_fmac_f32_e32 v43, v62, v26
	v_fmac_f32_e32 v42, v61, v26
	v_fmac_f32_e32 v41, v60, v26
	v_fmac_f32_e32 v40, v59, v26
	v_fmac_f32_e32 v39, v58, v26
	v_fmac_f32_e32 v38, v57, v26
	v_fmac_f32_e32 v37, v56, v26
	v_fmac_f32_e32 v36, v55, v26
	v_fmac_f32_e32 v33, v54, v26
	v_fma_f32 v26, v53, v26, v86
	v_fmac_f32_e32 v97, v84, v17
	v_fmac_f32_e32 v96, v83, v17
	v_fmac_f32_e32 v95, v82, v17
	v_fmac_f32_e32 v94, v81, v17
	v_fmac_f32_e32 v93, v80, v17
	v_fmac_f32_e32 v92, v79, v17
	v_fmac_f32_e32 v91, v78, v17
	v_fmac_f32_e32 v90, v77, v17
	v_fmac_f32_e32 v89, v76, v17
	v_fmac_f32_e32 v88, v75, v17
	v_fmac_f32_e32 v64, v74, v17
	v_fmac_f32_e32 v52, v73, v17
	v_fmac_f32_e32 v51, v72, v17
	v_fmac_f32_e32 v49, v71, v17
	v_fmac_f32_e32 v48, v70, v17
	v_fmac_f32_e32 v47, v69, v17
	v_fmac_f32_e32 v46, v68, v17
	v_fmac_f32_e32 v45, v67, v17
	v_fmac_f32_e32 v44, v66, v17
	v_fmac_f32_e32 v43, v63, v17
	v_fmac_f32_e32 v42, v62, v17
	v_fmac_f32_e32 v41, v61, v17
	v_fmac_f32_e32 v40, v60, v17
	v_fmac_f32_e32 v39, v59, v17
	v_fmac_f32_e32 v38, v58, v17
	v_fmac_f32_e32 v37, v57, v17
	v_fmac_f32_e32 v36, v56, v17
	v_fmac_f32_e32 v33, v55, v17
	v_fmac_f32_e32 v26, v54, v17
	v_fma_f32 v17, v53, v17, v86
	s_waitcnt lgkmcnt(0)
	v_lshlrev_b32_e32 v0, 16, v0
	v_fmac_f32_e32 v97, v85, v8
	v_fmac_f32_e32 v96, v84, v8
	v_fmac_f32_e32 v95, v83, v8
	v_fmac_f32_e32 v94, v82, v8
	v_fmac_f32_e32 v93, v81, v8
	v_fmac_f32_e32 v92, v80, v8
	v_fmac_f32_e32 v91, v79, v8
	v_fmac_f32_e32 v90, v78, v8
	v_fmac_f32_e32 v89, v77, v8
	v_fmac_f32_e32 v88, v76, v8
	v_fmac_f32_e32 v64, v75, v8
	v_fmac_f32_e32 v52, v74, v8
	v_fmac_f32_e32 v51, v73, v8
	v_fmac_f32_e32 v49, v72, v8
	v_fmac_f32_e32 v48, v71, v8
	v_fmac_f32_e32 v47, v70, v8
	v_fmac_f32_e32 v46, v69, v8
	v_fmac_f32_e32 v45, v68, v8
	v_fmac_f32_e32 v44, v67, v8
	v_fmac_f32_e32 v43, v66, v8
	v_fmac_f32_e32 v42, v63, v8
	v_fmac_f32_e32 v41, v62, v8
	v_fmac_f32_e32 v40, v61, v8
	v_fmac_f32_e32 v39, v60, v8
	v_fmac_f32_e32 v38, v59, v8
	v_fmac_f32_e32 v37, v58, v8
	v_fmac_f32_e32 v36, v57, v8
	v_fmac_f32_e32 v33, v56, v8
	v_fmac_f32_e32 v26, v55, v8
	v_fmac_f32_e32 v17, v54, v8
	v_fma_f32 v8, v53, v8, v86
	v_fmac_f32_e32 v96, v85, v0
	v_fmac_f32_e32 v95, v84, v0
	v_fmac_f32_e32 v94, v83, v0
	v_fmac_f32_e32 v93, v82, v0
	v_fmac_f32_e32 v92, v81, v0
	v_fmac_f32_e32 v91, v80, v0
	v_fmac_f32_e32 v90, v79, v0
	v_fmac_f32_e32 v89, v78, v0
	v_fmac_f32_e32 v88, v77, v0
	v_fmac_f32_e32 v64, v76, v0
	v_fmac_f32_e32 v52, v75, v0
	v_fmac_f32_e32 v51, v74, v0
	v_fmac_f32_e32 v49, v73, v0
	v_fmac_f32_e32 v48, v72, v0
	v_fmac_f32_e32 v47, v71, v0
	v_fmac_f32_e32 v46, v70, v0
	v_fmac_f32_e32 v45, v69, v0
	v_fmac_f32_e32 v44, v68, v0
	v_fmac_f32_e32 v43, v67, v0
	v_fmac_f32_e32 v42, v66, v0
	v_fmac_f32_e32 v41, v63, v0
	v_fmac_f32_e32 v40, v62, v0
	v_fmac_f32_e32 v39, v61, v0
	v_fmac_f32_e32 v38, v60, v0
	v_fmac_f32_e32 v37, v59, v0
	v_fmac_f32_e32 v36, v58, v0
	v_fmac_f32_e32 v33, v57, v0
	v_fmac_f32_e32 v26, v56, v0
	v_fmac_f32_e32 v17, v55, v0
	v_fmac_f32_e32 v8, v54, v0
	v_fma_f32 v0, v53, v0, v86
	v_fmac_f32_e32 v0, v54, v1
	v_lshlrev_b32_e32 v3, 16, v3
	v_fmac_f32_e32 v0, v55, v2
	v_lshlrev_b32_e32 v4, 16, v4
	v_fmac_f32_e32 v0, v56, v3
	v_lshlrev_b32_e32 v5, 16, v5
	v_fmac_f32_e32 v8, v55, v1
	v_fmac_f32_e32 v0, v57, v4
	v_lshlrev_b32_e32 v6, 16, v6
	v_fmac_f32_e32 v17, v56, v1
	v_fmac_f32_e32 v8, v56, v2
	v_fmac_f32_e32 v0, v58, v5
	v_lshlrev_b32_e32 v7, 16, v7
	v_fmac_f32_e32 v26, v57, v1
	v_fmac_f32_e32 v17, v57, v2
	v_fmac_f32_e32 v8, v57, v3
	v_fmac_f32_e32 v0, v59, v6
	v_lshlrev_b32_e32 v9, 16, v9
	v_fmac_f32_e32 v36, v59, v1
	v_fmac_f32_e32 v33, v58, v1
	v_fmac_f32_e32 v26, v58, v2
	v_fmac_f32_e32 v17, v58, v3
	v_fmac_f32_e32 v8, v58, v4
	v_fmac_f32_e32 v0, v60, v7
	v_lshlrev_b32_e32 v10, 16, v10
	v_fmac_f32_e32 v37, v60, v1
	v_fmac_f32_e32 v36, v60, v2
	v_fmac_f32_e32 v33, v59, v2
	v_fmac_f32_e32 v26, v59, v3
	v_fmac_f32_e32 v17, v59, v4
	v_fmac_f32_e32 v8, v59, v5
	v_fmac_f32_e32 v0, v61, v9
	v_lshlrev_b32_e32 v11, 16, v11
	v_fmac_f32_e32 v37, v61, v2
	v_fmac_f32_e32 v36, v61, v3
	v_fmac_f32_e32 v33, v60, v3
	v_fmac_f32_e32 v26, v60, v4
	v_fmac_f32_e32 v17, v60, v5
	v_fmac_f32_e32 v8, v60, v6
	v_fmac_f32_e32 v0, v62, v10
	v_lshlrev_b32_e32 v12, 16, v12
	v_fmac_f32_e32 v38, v61, v1
	v_fmac_f32_e32 v37, v62, v3
	v_fmac_f32_e32 v36, v62, v4
	v_fmac_f32_e32 v33, v61, v4
	v_fmac_f32_e32 v26, v61, v5
	v_fmac_f32_e32 v17, v61, v6
	v_fmac_f32_e32 v8, v61, v7
	v_fmac_f32_e32 v0, v63, v11
	v_lshlrev_b32_e32 v13, 16, v13
	v_fmac_f32_e32 v42, v67, v1
	v_fmac_f32_e32 v39, v62, v1
	v_fmac_f32_e32 v38, v62, v2
	v_fmac_f32_e32 v37, v63, v4
	v_fmac_f32_e32 v36, v63, v5
	v_fmac_f32_e32 v33, v62, v5
	v_fmac_f32_e32 v26, v62, v6
	v_fmac_f32_e32 v17, v62, v7
	v_fmac_f32_e32 v8, v62, v9
	v_fmac_f32_e32 v0, v66, v12
	v_lshlrev_b32_e32 v14, 16, v14
	v_fmac_f32_e32 v43, v68, v1
	v_fmac_f32_e32 v42, v68, v2
	v_fmac_f32_e32 v40, v63, v1
	v_fmac_f32_e32 v39, v63, v2
	v_fmac_f32_e32 v38, v63, v3
	v_fmac_f32_e32 v37, v66, v5
	v_fmac_f32_e32 v36, v66, v6
	v_fmac_f32_e32 v33, v63, v6
	v_fmac_f32_e32 v26, v63, v7
	v_fmac_f32_e32 v17, v63, v9
	v_fmac_f32_e32 v8, v63, v10
	v_fmac_f32_e32 v0, v67, v13
	v_lshlrev_b32_e32 v15, 16, v15
	v_fmac_f32_e32 v43, v69, v2
	v_fmac_f32_e32 v42, v69, v3
	v_fmac_f32_e32 v41, v66, v1
	v_fmac_f32_e32 v40, v66, v2
	v_fmac_f32_e32 v39, v66, v3
	v_fmac_f32_e32 v38, v66, v4
	v_fmac_f32_e32 v37, v67, v6
	v_fmac_f32_e32 v36, v67, v7
	v_fmac_f32_e32 v33, v66, v7
	v_fmac_f32_e32 v26, v66, v9
	v_fmac_f32_e32 v17, v66, v10
	v_fmac_f32_e32 v8, v66, v11
	v_fmac_f32_e32 v0, v68, v14
	v_lshlrev_b32_e32 v16, 16, v16
	v_fmac_f32_e32 v43, v70, v3
	v_fmac_f32_e32 v42, v70, v4
	v_fmac_f32_e32 v41, v67, v2
	v_fmac_f32_e32 v40, v67, v3
	v_fmac_f32_e32 v39, v67, v4
	v_fmac_f32_e32 v38, v67, v5
	v_fmac_f32_e32 v37, v68, v7
	v_fmac_f32_e32 v36, v68, v9
	v_fmac_f32_e32 v33, v67, v9
	v_fmac_f32_e32 v26, v67, v10
	v_fmac_f32_e32 v17, v67, v11
	v_fmac_f32_e32 v8, v67, v12
	v_fmac_f32_e32 v0, v69, v15
	v_lshlrev_b32_e32 v18, 16, v18
	v_fmac_f32_e32 v43, v71, v4
	v_fmac_f32_e32 v42, v71, v5
	v_fmac_f32_e32 v41, v68, v3
	v_fmac_f32_e32 v40, v68, v4
	v_fmac_f32_e32 v39, v68, v5
	v_fmac_f32_e32 v38, v68, v6
	v_fmac_f32_e32 v37, v69, v9
	v_fmac_f32_e32 v36, v69, v10
	v_fmac_f32_e32 v33, v68, v10
	v_fmac_f32_e32 v26, v68, v11
	v_fmac_f32_e32 v17, v68, v12
	v_fmac_f32_e32 v8, v68, v13
	v_fmac_f32_e32 v0, v70, v16
	v_lshlrev_b32_e32 v19, 16, v19
	v_fmac_f32_e32 v46, v71, v1
	v_fmac_f32_e32 v44, v69, v1
	v_fmac_f32_e32 v43, v72, v5
	v_fmac_f32_e32 v42, v72, v6
	v_fmac_f32_e32 v41, v69, v4
	v_fmac_f32_e32 v40, v69, v5
	v_fmac_f32_e32 v39, v69, v6
	v_fmac_f32_e32 v38, v69, v7
	v_fmac_f32_e32 v37, v70, v10
	v_fmac_f32_e32 v36, v70, v11
	v_fmac_f32_e32 v33, v69, v11
	v_fmac_f32_e32 v26, v69, v12
	v_fmac_f32_e32 v17, v69, v13
	v_fmac_f32_e32 v8, v69, v14
	v_fmac_f32_e32 v0, v71, v18
	v_lshlrev_b32_e32 v20, 16, v20
	v_fmac_f32_e32 v47, v72, v1
	v_fmac_f32_e32 v46, v72, v2
	v_fmac_f32_e32 v45, v70, v1
	v_fmac_f32_e32 v44, v70, v2
	v_fmac_f32_e32 v43, v73, v6
	v_fmac_f32_e32 v42, v73, v7
	v_fmac_f32_e32 v41, v70, v5
	v_fmac_f32_e32 v40, v70, v6
	v_fmac_f32_e32 v39, v70, v7
	v_fmac_f32_e32 v38, v70, v9
	v_fmac_f32_e32 v37, v71, v11
	v_fmac_f32_e32 v36, v71, v12
	v_fmac_f32_e32 v33, v70, v12
	v_fmac_f32_e32 v26, v70, v13
	v_fmac_f32_e32 v17, v70, v14
	v_fmac_f32_e32 v8, v70, v15
	v_fmac_f32_e32 v0, v72, v19
	v_lshlrev_b32_e32 v21, 16, v21
	v_fmac_f32_e32 v48, v73, v1
	v_fmac_f32_e32 v47, v73, v2
	v_fmac_f32_e32 v46, v73, v3
	v_fmac_f32_e32 v45, v71, v2
	v_fmac_f32_e32 v44, v71, v3
	v_fmac_f32_e32 v43, v74, v7
	v_fmac_f32_e32 v42, v74, v9
	v_fmac_f32_e32 v41, v71, v6
	v_fmac_f32_e32 v40, v71, v7
	v_fmac_f32_e32 v39, v71, v9
	v_fmac_f32_e32 v38, v71, v10
	v_fmac_f32_e32 v37, v72, v12
	v_fmac_f32_e32 v36, v72, v13
	v_fmac_f32_e32 v33, v71, v13
	v_fmac_f32_e32 v26, v71, v14
	v_fmac_f32_e32 v17, v71, v15
	v_fmac_f32_e32 v8, v71, v16
	v_fmac_f32_e32 v0, v73, v20
	v_lshlrev_b32_e32 v22, 16, v22
	v_fmac_f32_e32 v49, v74, v1
	v_fmac_f32_e32 v48, v74, v2
	v_fmac_f32_e32 v47, v74, v3
	v_fmac_f32_e32 v46, v74, v4
	v_fmac_f32_e32 v45, v72, v3
	v_fmac_f32_e32 v44, v72, v4
	v_fmac_f32_e32 v43, v75, v9
	v_fmac_f32_e32 v42, v75, v10
	v_fmac_f32_e32 v41, v72, v7
	v_fmac_f32_e32 v40, v72, v9
	v_fmac_f32_e32 v39, v72, v10
	v_fmac_f32_e32 v38, v72, v11
	v_fmac_f32_e32 v37, v73, v13
	v_fmac_f32_e32 v36, v73, v14
	v_fmac_f32_e32 v33, v72, v14
	v_fmac_f32_e32 v26, v72, v15
	v_fmac_f32_e32 v17, v72, v16
	v_fmac_f32_e32 v8, v72, v18
	v_fmac_f32_e32 v0, v74, v21
	v_lshlrev_b32_e32 v23, 16, v23
	v_fmac_f32_e32 v51, v75, v1
	v_fmac_f32_e32 v49, v75, v2
	v_fmac_f32_e32 v48, v75, v3
	v_fmac_f32_e32 v47, v75, v4
	v_fmac_f32_e32 v46, v75, v5
	v_fmac_f32_e32 v45, v73, v4
	v_fmac_f32_e32 v44, v73, v5
	v_fmac_f32_e32 v43, v76, v10
	v_fmac_f32_e32 v42, v76, v11
	v_fmac_f32_e32 v41, v73, v9
	v_fmac_f32_e32 v40, v73, v10
	v_fmac_f32_e32 v39, v73, v11
	v_fmac_f32_e32 v38, v73, v12
	v_fmac_f32_e32 v37, v74, v14
	v_fmac_f32_e32 v36, v74, v15
	v_fmac_f32_e32 v33, v73, v15
	v_fmac_f32_e32 v26, v73, v16
	v_fmac_f32_e32 v17, v73, v18
	v_fmac_f32_e32 v8, v73, v19
	v_fmac_f32_e32 v0, v75, v22
	v_lshlrev_b32_e32 v24, 16, v24
	v_fmac_f32_e32 v52, v76, v1
	v_fmac_f32_e32 v51, v76, v2
	v_fmac_f32_e32 v49, v76, v3
	v_fmac_f32_e32 v48, v76, v4
	v_fmac_f32_e32 v47, v76, v5
	v_fmac_f32_e32 v46, v76, v6
	v_fmac_f32_e32 v45, v74, v5
	v_fmac_f32_e32 v44, v74, v6
	v_fmac_f32_e32 v43, v77, v11
	v_fmac_f32_e32 v42, v77, v12
	v_fmac_f32_e32 v41, v74, v10
	v_fmac_f32_e32 v40, v74, v11
	v_fmac_f32_e32 v39, v74, v12
	v_fmac_f32_e32 v38, v74, v13
	v_fmac_f32_e32 v37, v75, v15
	v_fmac_f32_e32 v36, v75, v16
	v_fmac_f32_e32 v33, v74, v16
	v_fmac_f32_e32 v26, v74, v18
	v_fmac_f32_e32 v17, v74, v19
	v_fmac_f32_e32 v8, v74, v20
	v_fmac_f32_e32 v0, v76, v23
	v_lshlrev_b32_e32 v25, 16, v25
	v_fmac_f32_e32 v64, v77, v1
	v_fmac_f32_e32 v52, v77, v2
	v_fmac_f32_e32 v51, v77, v3
	v_fmac_f32_e32 v49, v77, v4
	v_fmac_f32_e32 v48, v77, v5
	v_fmac_f32_e32 v47, v77, v6
	v_fmac_f32_e32 v46, v77, v7
	v_fmac_f32_e32 v45, v75, v6
	v_fmac_f32_e32 v44, v75, v7
	v_fmac_f32_e32 v43, v78, v12
	v_fmac_f32_e32 v42, v78, v13
	v_fmac_f32_e32 v41, v75, v11
	v_fmac_f32_e32 v40, v75, v12
	v_fmac_f32_e32 v39, v75, v13
	v_fmac_f32_e32 v38, v75, v14
	v_fmac_f32_e32 v37, v76, v16
	v_fmac_f32_e32 v36, v76, v18
	v_fmac_f32_e32 v33, v75, v18
	v_fmac_f32_e32 v26, v75, v19
	v_fmac_f32_e32 v17, v75, v20
	v_fmac_f32_e32 v8, v75, v21
	v_fmac_f32_e32 v0, v77, v24
	v_lshlrev_b32_e32 v27, 16, v27
	v_fmac_f32_e32 v88, v78, v1
	v_fmac_f32_e32 v64, v78, v2
	v_fmac_f32_e32 v52, v78, v3
	v_fmac_f32_e32 v51, v78, v4
	v_fmac_f32_e32 v49, v78, v5
	v_fmac_f32_e32 v48, v78, v6
	v_fmac_f32_e32 v47, v78, v7
	v_fmac_f32_e32 v46, v78, v9
	v_fmac_f32_e32 v45, v76, v7
	v_fmac_f32_e32 v44, v76, v9
	v_fmac_f32_e32 v43, v79, v13
	v_fmac_f32_e32 v42, v79, v14
	v_fmac_f32_e32 v41, v76, v12
	v_fmac_f32_e32 v40, v76, v13
	v_fmac_f32_e32 v39, v76, v14
	v_fmac_f32_e32 v38, v76, v15
	v_fmac_f32_e32 v37, v77, v18
	v_fmac_f32_e32 v36, v77, v19
	v_fmac_f32_e32 v33, v76, v19
	v_fmac_f32_e32 v26, v76, v20
	v_fmac_f32_e32 v17, v76, v21
	v_fmac_f32_e32 v8, v76, v22
	v_fmac_f32_e32 v0, v78, v25
	v_lshlrev_b32_e32 v28, 16, v28
	ds_read_u16 v34, v34 offset:31232
	v_fmac_f32_e32 v89, v79, v1
	v_fmac_f32_e32 v88, v79, v2
	v_fmac_f32_e32 v64, v79, v3
	v_fmac_f32_e32 v52, v79, v4
	v_fmac_f32_e32 v51, v79, v5
	v_fmac_f32_e32 v49, v79, v6
	v_fmac_f32_e32 v48, v79, v7
	v_fmac_f32_e32 v47, v79, v9
	v_fmac_f32_e32 v46, v79, v10
	v_fmac_f32_e32 v45, v77, v9
	v_fmac_f32_e32 v44, v77, v10
	v_fmac_f32_e32 v43, v80, v14
	v_fmac_f32_e32 v42, v80, v15
	v_fmac_f32_e32 v41, v77, v13
	v_fmac_f32_e32 v40, v77, v14
	v_fmac_f32_e32 v39, v77, v15
	v_fmac_f32_e32 v38, v77, v16
	v_fmac_f32_e32 v37, v78, v19
	v_fmac_f32_e32 v36, v78, v20
	v_fmac_f32_e32 v33, v77, v20
	v_fmac_f32_e32 v26, v77, v21
	v_fmac_f32_e32 v17, v77, v22
	v_fmac_f32_e32 v8, v77, v23
	v_fmac_f32_e32 v0, v79, v27
	v_lshlrev_b32_e32 v29, 16, v29
	v_fmac_f32_e32 v90, v80, v1
	v_fmac_f32_e32 v89, v80, v2
	v_fmac_f32_e32 v88, v80, v3
	v_fmac_f32_e32 v64, v80, v4
	v_fmac_f32_e32 v52, v80, v5
	v_fmac_f32_e32 v51, v80, v6
	v_fmac_f32_e32 v49, v80, v7
	v_fmac_f32_e32 v48, v80, v9
	v_fmac_f32_e32 v47, v80, v10
	v_fmac_f32_e32 v46, v80, v11
	v_fmac_f32_e32 v45, v78, v10
	v_fmac_f32_e32 v44, v78, v11
	v_fmac_f32_e32 v43, v81, v15
	v_fmac_f32_e32 v42, v81, v16
	v_fmac_f32_e32 v41, v78, v14
	v_fmac_f32_e32 v40, v78, v15
	v_fmac_f32_e32 v39, v78, v16
	v_fmac_f32_e32 v38, v78, v18
	v_fmac_f32_e32 v37, v79, v20
	v_fmac_f32_e32 v36, v79, v21
	v_fmac_f32_e32 v33, v78, v21
	v_fmac_f32_e32 v26, v78, v22
	v_fmac_f32_e32 v17, v78, v23
	v_fmac_f32_e32 v8, v78, v24
	v_fmac_f32_e32 v0, v80, v28
	v_lshlrev_b32_e32 v30, 16, v30
	v_fmac_f32_e32 v91, v81, v1
	v_fmac_f32_e32 v90, v81, v2
	v_fmac_f32_e32 v89, v81, v3
	v_fmac_f32_e32 v88, v81, v4
	v_fmac_f32_e32 v64, v81, v5
	v_fmac_f32_e32 v52, v81, v6
	v_fmac_f32_e32 v51, v81, v7
	v_fmac_f32_e32 v49, v81, v9
	v_fmac_f32_e32 v48, v81, v10
	v_fmac_f32_e32 v47, v81, v11
	v_fmac_f32_e32 v46, v81, v12
	v_fmac_f32_e32 v45, v79, v11
	v_fmac_f32_e32 v44, v79, v12
	v_fmac_f32_e32 v43, v82, v16
	v_fmac_f32_e32 v42, v82, v18
	v_fmac_f32_e32 v41, v79, v15
	v_fmac_f32_e32 v40, v79, v16
	v_fmac_f32_e32 v39, v79, v18
	v_fmac_f32_e32 v38, v79, v19
	v_fmac_f32_e32 v37, v80, v21
	v_fmac_f32_e32 v36, v80, v22
	v_fmac_f32_e32 v33, v79, v22
	v_fmac_f32_e32 v26, v79, v23
	v_fmac_f32_e32 v17, v79, v24
	v_fmac_f32_e32 v8, v79, v25
	v_fmac_f32_e32 v0, v81, v29
	v_lshlrev_b32_e32 v31, 16, v31
	v_fmac_f32_e32 v92, v82, v1
	v_fmac_f32_e32 v91, v82, v2
	v_fmac_f32_e32 v90, v82, v3
	v_fmac_f32_e32 v89, v82, v4
	v_fmac_f32_e32 v88, v82, v5
	v_fmac_f32_e32 v64, v82, v6
	v_fmac_f32_e32 v52, v82, v7
	v_fmac_f32_e32 v51, v82, v9
	v_fmac_f32_e32 v49, v82, v10
	v_fmac_f32_e32 v48, v82, v11
	v_fmac_f32_e32 v47, v82, v12
	v_fmac_f32_e32 v46, v82, v13
	v_fmac_f32_e32 v45, v80, v12
	v_fmac_f32_e32 v44, v80, v13
	v_fmac_f32_e32 v43, v83, v18
	v_fmac_f32_e32 v42, v83, v19
	v_fmac_f32_e32 v41, v80, v16
	v_fmac_f32_e32 v40, v80, v18
	v_fmac_f32_e32 v39, v80, v19
	v_fmac_f32_e32 v38, v80, v20
	v_fmac_f32_e32 v37, v81, v22
	v_fmac_f32_e32 v36, v81, v23
	v_fmac_f32_e32 v33, v80, v23
	v_fmac_f32_e32 v26, v80, v24
	v_fmac_f32_e32 v17, v80, v25
	v_fmac_f32_e32 v8, v80, v27
	v_fmac_f32_e32 v0, v82, v30
	v_lshlrev_b32_e32 v32, 16, v32
	v_add3_u32 v87, 0, v35, v87
	v_fmac_f32_e32 v93, v83, v1
	v_fmac_f32_e32 v92, v83, v2
	v_fmac_f32_e32 v91, v83, v3
	v_fmac_f32_e32 v90, v83, v4
	v_fmac_f32_e32 v89, v83, v5
	v_fmac_f32_e32 v88, v83, v6
	v_fmac_f32_e32 v64, v83, v7
	v_fmac_f32_e32 v52, v83, v9
	v_fmac_f32_e32 v51, v83, v10
	v_fmac_f32_e32 v49, v83, v11
	v_fmac_f32_e32 v48, v83, v12
	v_fmac_f32_e32 v47, v83, v13
	v_fmac_f32_e32 v46, v83, v14
	v_fmac_f32_e32 v45, v81, v13
	v_fmac_f32_e32 v44, v81, v14
	v_fmac_f32_e32 v43, v84, v19
	v_fmac_f32_e32 v42, v84, v20
	v_fmac_f32_e32 v41, v81, v18
	v_fmac_f32_e32 v40, v81, v19
	v_fmac_f32_e32 v39, v81, v20
	v_fmac_f32_e32 v38, v81, v21
	v_fmac_f32_e32 v37, v82, v23
	v_fmac_f32_e32 v36, v82, v24
	v_fmac_f32_e32 v33, v81, v24
	v_fmac_f32_e32 v26, v81, v25
	v_fmac_f32_e32 v17, v81, v27
	v_fmac_f32_e32 v8, v81, v28
	v_fmac_f32_e32 v0, v83, v31
	s_waitcnt lgkmcnt(0)
	v_lshlrev_b32_e32 v34, 16, v34
	v_add_u32_e32 v35, 0xbc00, v87
	v_fmac_f32_e32 v95, v85, v1
	v_fmac_f32_e32 v94, v84, v1
	v_fmac_f32_e32 v93, v84, v2
	v_fmac_f32_e32 v92, v84, v3
	v_fmac_f32_e32 v91, v84, v4
	v_fmac_f32_e32 v90, v84, v5
	v_fmac_f32_e32 v89, v84, v6
	v_fmac_f32_e32 v88, v84, v7
	v_fmac_f32_e32 v64, v84, v9
	v_fmac_f32_e32 v52, v84, v10
	v_fmac_f32_e32 v51, v84, v11
	v_fmac_f32_e32 v49, v84, v12
	v_fmac_f32_e32 v48, v84, v13
	v_fmac_f32_e32 v47, v84, v14
	v_fmac_f32_e32 v46, v84, v15
	v_fmac_f32_e32 v45, v82, v14
	v_fmac_f32_e32 v44, v82, v15
	v_fmac_f32_e32 v43, v85, v20
	v_fmac_f32_e32 v42, v85, v21
	v_fmac_f32_e32 v41, v82, v19
	v_fmac_f32_e32 v40, v82, v20
	v_fmac_f32_e32 v39, v82, v21
	v_fmac_f32_e32 v38, v82, v22
	v_fmac_f32_e32 v37, v83, v24
	v_fmac_f32_e32 v36, v83, v25
	v_fmac_f32_e32 v33, v82, v25
	v_fmac_f32_e32 v26, v82, v27
	v_fmac_f32_e32 v17, v82, v28
	v_fmac_f32_e32 v8, v82, v29
	v_fmac_f32_e32 v0, v84, v32
	v_lshlrev_b32_e32 v1, 5, v50
	v_fmac_f32_e32 v94, v85, v2
	v_fmac_f32_e32 v93, v85, v3
	v_fmac_f32_e32 v92, v85, v4
	v_fmac_f32_e32 v91, v85, v5
	v_fmac_f32_e32 v90, v85, v6
	v_fmac_f32_e32 v89, v85, v7
	v_fmac_f32_e32 v88, v85, v9
	v_fmac_f32_e32 v64, v85, v10
	v_fmac_f32_e32 v52, v85, v11
	v_fmac_f32_e32 v51, v85, v12
	v_fmac_f32_e32 v49, v85, v13
	v_fmac_f32_e32 v48, v85, v14
	v_fmac_f32_e32 v47, v85, v15
	v_fmac_f32_e32 v46, v85, v16
	v_fmac_f32_e32 v45, v83, v15
	v_fmac_f32_e32 v44, v83, v16
	ds_write2st64_b32 v35, v43, v42 offset0:76 offset1:80
	v_fmac_f32_e32 v41, v83, v20
	v_fmac_f32_e32 v40, v83, v21
	v_fmac_f32_e32 v39, v83, v22
	v_fmac_f32_e32 v38, v83, v23
	v_fmac_f32_e32 v37, v84, v25
	v_fmac_f32_e32 v36, v84, v27
	v_fmac_f32_e32 v33, v83, v27
	v_fmac_f32_e32 v26, v83, v28
	v_fmac_f32_e32 v17, v83, v29
	v_fmac_f32_e32 v8, v83, v30
	v_fmac_f32_e32 v0, v85, v34
	v_ashrrev_i32_e32 v42, 3, v50
	v_and_b32_e32 v43, 0xe0, v1
	ds_write2st64_b32 v87, v97, v96 offset0:188 offset1:192
	ds_write2st64_b32 v87, v95, v94 offset0:196 offset1:200
	ds_write2st64_b32 v87, v93, v92 offset0:204 offset1:208
	ds_write2st64_b32 v87, v91, v90 offset0:212 offset1:216
	ds_write2st64_b32 v87, v89, v88 offset0:220 offset1:224
	ds_write2st64_b32 v87, v64, v52 offset0:228 offset1:232
	ds_write2st64_b32 v87, v51, v49 offset0:236 offset1:240
	ds_write2st64_b32 v87, v48, v47 offset0:244 offset1:248
	ds_write_b32 v87, v46 offset:64512
	v_fmac_f32_e32 v45, v84, v16
	v_fmac_f32_e32 v44, v84, v18
	v_fmac_f32_e32 v41, v84, v21
	v_fmac_f32_e32 v40, v84, v22
	v_fmac_f32_e32 v39, v84, v23
	v_fmac_f32_e32 v38, v84, v24
	v_fmac_f32_e32 v37, v85, v27
	v_fmac_f32_e32 v36, v85, v28
	v_fmac_f32_e32 v33, v84, v28
	v_fmac_f32_e32 v26, v84, v29
	v_fmac_f32_e32 v17, v84, v30
	v_fmac_f32_e32 v8, v84, v31
	ds_write_b32 v35, v0 offset:31744
	v_lshlrev_b32_e32 v0, 10, v42
	v_lshlrev_b32_e32 v87, 2, v43
	global_load_dwordx4 v[104:107], v87, s[22:23] offset:16
	global_load_dwordx4 v[108:111], v87, s[22:23]
	global_load_dwordx4 v[118:121], v87, s[2:3] offset:16
	global_load_dwordx4 v[122:125], v87, s[2:3]
	global_load_dwordx4 v[126:129], v87, s[22:23] offset:48
	global_load_dwordx4 v[134:137], v87, s[22:23] offset:32
	global_load_dwordx4 v[138:141], v87, s[2:3] offset:48
	global_load_dwordx4 v[142:145], v87, s[2:3] offset:32
	global_load_dwordx4 v[146:149], v87, s[22:23] offset:80
	global_load_dwordx4 v[150:153], v87, s[22:23] offset:64
	global_load_dwordx4 v[154:157], v87, s[2:3] offset:80
	global_load_dwordx4 v[160:163], v87, s[2:3] offset:64
	global_load_dwordx4 v[168:171], v87, s[22:23] offset:112
	global_load_dwordx4 v[172:175], v87, s[22:23] offset:96
	global_load_dwordx4 v[176:179], v87, s[2:3] offset:112
	global_load_dwordx4 v[184:187], v87, s[2:3] offset:96
	v_fmac_f32_e32 v45, v85, v18
	v_fmac_f32_e32 v44, v85, v19
	v_fmac_f32_e32 v41, v85, v22
	v_fmac_f32_e32 v40, v85, v23
	v_fmac_f32_e32 v39, v85, v24
	v_fmac_f32_e32 v38, v85, v25
	ds_write2st64_b32 v35, v37, v36 offset0:100 offset1:104
	v_fmac_f32_e32 v33, v85, v29
	v_fmac_f32_e32 v26, v85, v30
	v_fmac_f32_e32 v17, v85, v31
	v_fmac_f32_e32 v8, v85, v32
	v_add3_u32 v37, 0, v0, v87
	ds_write2st64_b32 v35, v45, v44 offset0:68 offset1:72
	ds_write2st64_b32 v35, v41, v40 offset0:84 offset1:88
	ds_write2st64_b32 v35, v39, v38 offset0:92 offset1:96
	ds_write2st64_b32 v35, v33, v26 offset0:108 offset1:112
	ds_write2st64_b32 v35, v17, v8 offset0:116 offset1:120
	s_waitcnt lgkmcnt(0)
	s_barrier
	ds_read_b128 v[28:31], v37 offset:48128
	ds_read_b128 v[24:27], v37 offset:48144
	ds_read_b128 v[20:23], v37 offset:48160
	ds_read_b128 v[16:19], v37 offset:48176
	s_mov_b32 s0, 0x3b800000
	s_waitcnt lgkmcnt(3)
	v_pk_mul_f32 v[0:1], v[30:31], v[30:31]
	v_pk_mul_f32 v[2:3], v[28:29], v[28:29]
	v_mov_b32_e32 v6, v31
	v_pk_mov_b32 v[4:5], v[2:3], v[0:1] op_sel:[1,0]
	v_mov_b32_e32 v3, v1
	v_pk_add_f32 v[0:1], v[4:5], v[2:3]
	v_mov_b32_e32 v2, v28
	s_waitcnt lgkmcnt(2)
	v_mov_b32_e32 v3, v24
	v_mov_b32_e32 v4, v29
	v_mov_b32_e32 v5, v25
	v_pk_add_f32 v[2:3], v[2:3], v[4:5]
	v_mov_b32_e32 v4, v30
	v_mov_b32_e32 v5, v26
	v_mov_b32_e32 v7, v27
	v_pk_add_f32 v[4:5], v[4:5], v[6:7]
	v_pk_mul_f32 v[6:7], v[24:25], v[24:25]
	v_pk_add_f32 v[2:3], v[2:3], v[4:5]
	v_pk_mul_f32 v[4:5], v[26:27], v[26:27]
	v_add_f32_e32 v2, 0, v2
	v_pk_mov_b32 v[8:9], v[6:7], v[4:5] op_sel:[1,0]
	v_mov_b32_e32 v7, v5
	v_pk_add_f32 v[4:5], v[8:9], v[6:7]
	s_waitcnt lgkmcnt(1)
	v_mov_b32_e32 v6, v21
	v_mov_b32_e32 v7, v22
	v_mov_b32_e32 v8, v20
	v_mov_b32_e32 v9, v23
	v_pk_add_f32 v[6:7], v[6:7], v[8:9]
	v_add_f32_e32 v2, v2, v3
	v_pk_add_f32 v[6:7], v[6:7], v[6:7] op_sel:[0,1] op_sel_hi:[1,0]
	s_waitcnt lgkmcnt(0)
	v_mul_f32_e32 v3, v16, v16
	v_mul_f32_e32 v7, v17, v17
	v_pk_add_f32 v[0:1], v[0:1], v[0:1] op_sel:[0,1] op_sel_hi:[1,0]
	v_pk_add_f32 v[4:5], v[4:5], v[4:5] op_sel:[0,1] op_sel_hi:[1,0]
	v_mov_b32_e32 v1, v3
	v_mov_b32_e32 v5, v7
	v_pk_add_f32 v[0:1], v[0:1], v[4:5]
	v_mul_f32_e32 v4, v21, v21
	v_mul_f32_e32 v12, v23, v23
	v_mul_f32_e32 v9, v18, v18
	v_mul_f32_e32 v11, v19, v19
	v_pk_fma_f32 v[4:5], v[20:21], v[20:21], v[4:5] op_sel_hi:[1,1,0]
	v_pk_fma_f32 v[12:13], v[22:23], v[22:23], v[12:13] op_sel_hi:[1,1,0]
	v_mov_b32_e32 v5, v9
	v_mov_b32_e32 v13, v11
	v_pk_add_f32 v[4:5], v[4:5], v[12:13]
	ds_read_b128 v[12:15], v37 offset:48192
	v_add_f32_e32 v8, v16, v17
	v_add_f32_e32 v10, v18, v19
	v_pk_add_f32 v[0:1], v[0:1], v[4:5]
	v_lshlrev_b32_e32 v64, 1, v43
	s_waitcnt lgkmcnt(0)
	v_mov_b32_e32 v9, v14
	v_mov_b32_e32 v11, v15
	v_mov_b32_e32 v3, v12
	v_mov_b32_e32 v7, v13
	v_pk_add_f32 v[4:5], v[8:9], v[10:11]
	ds_read_b128 v[8:11], v37 offset:48208
	v_pk_add_f32 v[2:3], v[2:3], v[6:7]
	v_pk_add_f32 v[0:1], v[0:1], v[0:1] op_sel:[0,1] op_sel_hi:[1,0]
	v_pk_add_f32 v[2:3], v[2:3], v[4:5]
	v_pk_mul_f32 v[4:5], v[12:13], v[12:13]
	v_pk_add_f32 v[32:33], v[2:3], v[2:3] op_sel:[0,1] op_sel_hi:[1,0]
	v_pk_mul_f32 v[2:3], v[14:15], v[14:15]
	s_waitcnt lgkmcnt(0)
	v_mul_f32_e32 v40, v11, v11
	v_pk_mov_b32 v[6:7], v[4:5], v[2:3] op_sel:[1,0]
	v_mov_b32_e32 v5, v3
	v_pk_add_f32 v[2:3], v[6:7], v[4:5]
	v_mov_b32_e32 v4, v9
	v_mov_b32_e32 v5, v10
	v_mov_b32_e32 v6, v8
	v_mov_b32_e32 v7, v11
	v_pk_add_f32 v[4:5], v[4:5], v[6:7]
	v_pk_add_f32 v[2:3], v[2:3], v[2:3] op_sel:[0,1] op_sel_hi:[1,0]
	v_pk_add_f32 v[34:35], v[4:5], v[4:5] op_sel:[0,1] op_sel_hi:[1,0]
	ds_read_b128 v[4:7], v37 offset:48224
	v_pk_fma_f32 v[40:41], v[10:11], v[10:11], v[40:41] op_sel_hi:[1,1,0]
	s_add_i32 s67, s67, s10
	s_waitcnt lgkmcnt(0)
	v_mul_f32_e32 v33, v4, v4
	v_mul_f32_e32 v35, v5, v5
	v_mov_b32_e32 v1, v33
	v_mov_b32_e32 v3, v35
	v_pk_add_f32 v[0:1], v[0:1], v[2:3]
	v_mul_f32_e32 v2, v9, v9
	v_mul_f32_e32 v39, v6, v6
	v_mul_f32_e32 v44, v7, v7
	v_pk_fma_f32 v[2:3], v[8:9], v[8:9], v[2:3] op_sel_hi:[1,1,0]
	v_mov_b32_e32 v41, v44
	v_mov_b32_e32 v3, v39
	v_pk_add_f32 v[2:3], v[2:3], v[40:41]
	v_add_f32_e32 v36, v4, v5
	v_pk_add_f32 v[0:1], v[0:1], v[2:3]
	v_add_f32_e32 v38, v6, v7
	v_pk_add_f32 v[40:41], v[0:1], v[0:1] op_sel:[0,1] op_sel_hi:[1,0]
	ds_read_b128 v[0:3], v37 offset:48240
	s_waitcnt lgkmcnt(0)
	v_mov_b32_e32 v33, v0
	v_mov_b32_e32 v35, v1
	v_mov_b32_e32 v37, v2
	v_mov_b32_e32 v39, v3
	v_pk_add_f32 v[32:33], v[32:33], v[34:35]
	v_pk_add_f32 v[34:35], v[36:37], v[38:39]
	v_pk_mul_f32 v[36:37], v[0:1], v[0:1]
	v_pk_add_f32 v[32:33], v[32:33], v[34:35]
	v_pk_mul_f32 v[34:35], v[2:3], v[2:3]
	v_mov_b32_e32 v41, v32
	v_pk_mov_b32 v[38:39], v[36:37], v[34:35] op_sel:[1,0]
	v_mov_b32_e32 v37, v35
	v_pk_add_f32 v[34:35], v[38:39], v[36:37]
	s_nop 0
	v_pk_add_f32 v[34:35], v[34:35], v[34:35] op_sel:[0,1] op_sel_hi:[1,0]
	s_nop 0
	v_mov_b32_e32 v35, v33
	v_pk_add_f32 v[32:33], v[40:41], v[34:35]
	ds_swizzle_b32 v35, v33 offset:swizzle(SWAP,1)
	ds_swizzle_b32 v34, v32 offset:swizzle(SWAP,1)
	s_waitcnt lgkmcnt(0)
	v_pk_add_f32 v[32:33], v[32:33], v[34:35]
	ds_swizzle_b32 v35, v33 offset:swizzle(SWAP,2)
	ds_swizzle_b32 v34, v32 offset:swizzle(SWAP,2)
	s_waitcnt lgkmcnt(0)
	v_pk_add_f32 v[32:33], v[32:33], v[34:35]
	ds_swizzle_b32 v35, v33 offset:swizzle(SWAP,4)
	ds_swizzle_b32 v34, v32 offset:swizzle(SWAP,4)
	s_waitcnt lgkmcnt(0)
	v_pk_add_f32 v[32:33], v[32:33], v[34:35]
	s_nop 0
	v_pk_mul_f32 v[50:51], v[32:33], s[0:1] op_sel_hi:[1,0]
	s_mov_b32 s0, 0x800000
	v_fma_f32 v32, -v51, v51, v50
	v_max_f32_e32 v32, 0, v32
	v_add_f32_e32 v32, 0x3727c5ac, v32
	v_cmp_gt_f32_e32 vcc, s0, v32
	v_mul_f32_e32 v33, 0x4b800000, v32
	v_pk_add_f32 v[28:29], v[28:29], v[50:51] op_sel:[0,1] neg_lo:[0,1] neg_hi:[0,1]
	v_cndmask_b32_e32 v32, v32, v33, vcc
	v_rsq_f32_e32 v32, v32
	v_pk_add_f32 v[24:25], v[24:25], v[50:51] op_sel:[0,1] neg_lo:[0,1] neg_hi:[0,1]
	v_pk_add_f32 v[20:21], v[20:21], v[50:51] op_sel:[0,1] neg_lo:[0,1] neg_hi:[0,1]
	v_pk_add_f32 v[16:17], v[16:17], v[50:51] op_sel:[0,1] neg_lo:[0,1] neg_hi:[0,1]
	v_mul_f32_e32 v33, 0x45800000, v32
	v_cndmask_b32_e32 v52, v32, v33, vcc
	v_add3_u32 v32, s34, v42, 15
	v_ashrrev_i32_e32 v33, 31, v32
	v_lshlrev_b64 v[32:33], 11, v[32:33]
	v_lshl_add_u64 v[32:33], s[8:9], 0, v[32:33]
	v_lshl_add_u64 v[48:49], v[32:33], 0, v[64:65]
	v_pk_mul_f32 v[28:29], v[28:29], v[52:53] op_sel_hi:[1,0]
	v_pk_mul_f32 v[24:25], v[24:25], v[52:53] op_sel_hi:[1,0]
	v_pk_mul_f32 v[20:21], v[20:21], v[52:53] op_sel_hi:[1,0]
	v_pk_mul_f32 v[16:17], v[16:17], v[52:53] op_sel_hi:[1,0]
	v_pk_add_f32 v[12:13], v[12:13], v[50:51] op_sel:[0,1] neg_lo:[0,1] neg_hi:[0,1]
	v_pk_add_f32 v[8:9], v[8:9], v[50:51] op_sel:[0,1] neg_lo:[0,1] neg_hi:[0,1]
	v_pk_mul_f32 v[12:13], v[12:13], v[52:53] op_sel_hi:[1,0]
	v_pk_mul_f32 v[8:9], v[8:9], v[52:53] op_sel_hi:[1,0]
	v_pk_add_f32 v[4:5], v[4:5], v[50:51] op_sel:[0,1] neg_lo:[0,1] neg_hi:[0,1]
	v_pk_add_f32 v[0:1], v[0:1], v[50:51] op_sel:[0,1] neg_lo:[0,1] neg_hi:[0,1]
	v_pk_mul_f32 v[4:5], v[4:5], v[52:53] op_sel_hi:[1,0]
	v_pk_mul_f32 v[0:1], v[0:1], v[52:53] op_sel_hi:[1,0]
	s_add_i32 s34, s34, s13
	s_cmpk_lt_i32 s67, 0x100
	s_waitcnt vmcnt(0)
	v_pk_fma_f32 v[24:25], v[104:105], v[24:25], v[118:119]
	v_pk_fma_f32 v[28:29], v[108:109], v[28:29], v[122:123]
	s_nop 0
	v_mul_f32_e32 v40, 0xbfb8aa3b, v28
	v_mul_f32_e32 v41, 0xbfb8aa3b, v29
	v_exp_f32_e32 v40, v40
	v_exp_f32_e32 v41, v41
	s_nop 0
	v_pk_add_f32 v[40:41], v[40:41], 1.0 op_sel_hi:[1,0]
	s_nop 0
	v_div_scale_f32 v44, s[0:1], v41, v41, v29
	v_rcp_f32_e32 v45, v44
	s_nop 0
	v_fma_f32 v64, -v44, v45, 1.0
	v_fmac_f32_e32 v45, v64, v45
	v_div_scale_f32 v64, vcc, v29, v41, v29
	v_mul_f32_e32 v88, v64, v45
	v_fma_f32 v89, -v44, v88, v64
	v_fmac_f32_e32 v88, v89, v45
	v_fma_f32 v44, -v44, v88, v64
	v_div_fmas_f32 v44, v44, v45, v88
	v_div_fixup_f32 v41, v44, v41, v29
	v_div_scale_f32 v29, s[0:1], v40, v40, v28
	v_rcp_f32_e32 v44, v29
	s_nop 0
	v_fma_f32 v45, -v29, v44, 1.0
	v_fmac_f32_e32 v44, v45, v44
	v_div_scale_f32 v45, vcc, v28, v40, v28
	v_mul_f32_e32 v64, v45, v44
	v_fma_f32 v88, -v29, v64, v45
	v_fmac_f32_e32 v64, v88, v44
	v_fma_f32 v29, -v29, v64, v45
	v_div_fmas_f32 v29, v29, v44, v64
	v_div_fixup_f32 v40, v29, v40, v28
	v_pk_add_f32 v[28:29], v[30:31], v[50:51] op_sel:[0,1] neg_lo:[0,1] neg_hi:[0,1]
	s_nop 0
	v_pk_mul_f32 v[28:29], v[28:29], v[52:53] op_sel_hi:[1,0]
	s_nop 0
	v_pk_fma_f32 v[28:29], v[110:111], v[28:29], v[124:125]
	s_nop 0
	v_mul_f32_e32 v30, 0xbfb8aa3b, v28
	v_mul_f32_e32 v31, 0xbfb8aa3b, v29
	v_exp_f32_e32 v30, v30
	v_exp_f32_e32 v31, v31
	s_nop 0
	v_pk_add_f32 v[30:31], v[30:31], 1.0 op_sel_hi:[1,0]
	s_nop 0
	v_div_scale_f32 v42, s[0:1], v31, v31, v29
	v_rcp_f32_e32 v43, v42
	s_nop 0
	v_fma_f32 v44, -v42, v43, 1.0
	v_fmac_f32_e32 v43, v44, v43
	v_div_scale_f32 v44, vcc, v29, v31, v29
	v_mul_f32_e32 v45, v44, v43
	v_fma_f32 v46, -v42, v45, v44
	v_fmac_f32_e32 v45, v46, v43
	v_fma_f32 v42, -v42, v45, v44
	v_div_fmas_f32 v42, v42, v43, v45
	v_div_fixup_f32 v31, v42, v31, v29
	v_div_scale_f32 v29, s[0:1], v30, v30, v28
	v_rcp_f32_e32 v42, v29
	s_nop 0
	v_fma_f32 v43, -v29, v42, 1.0
	v_fmac_f32_e32 v42, v43, v42
	v_div_scale_f32 v43, vcc, v28, v30, v28
	v_mul_f32_e32 v44, v43, v42
	v_fma_f32 v45, -v29, v44, v43
	v_fmac_f32_e32 v44, v45, v42
	v_fma_f32 v29, -v29, v44, v43
	v_div_fmas_f32 v29, v29, v42, v44
	v_div_fixup_f32 v30, v29, v30, v28
	v_mul_f32_e32 v28, 0xbfb8aa3b, v24
	v_mul_f32_e32 v29, 0xbfb8aa3b, v25
	v_exp_f32_e32 v28, v28
	v_exp_f32_e32 v29, v29
	s_nop 0
	v_pk_add_f32 v[28:29], v[28:29], 1.0 op_sel_hi:[1,0]
	s_nop 0
	v_div_scale_f32 v32, s[0:1], v29, v29, v25
	v_rcp_f32_e32 v33, v32
	s_nop 0
	v_fma_f32 v36, -v32, v33, 1.0
	v_fmac_f32_e32 v33, v36, v33
	v_div_scale_f32 v36, vcc, v25, v29, v25
	v_mul_f32_e32 v37, v36, v33
	v_fma_f32 v42, -v32, v37, v36
	v_fmac_f32_e32 v37, v42, v33
	v_fma_f32 v32, -v32, v37, v36
	v_div_fmas_f32 v32, v32, v33, v37
	v_div_fixup_f32 v29, v32, v29, v25
	v_div_scale_f32 v25, s[0:1], v28, v28, v24
	v_rcp_f32_e32 v32, v25
	s_nop 0
	v_fma_f32 v33, -v25, v32, 1.0
	v_fmac_f32_e32 v32, v33, v32
	v_div_scale_f32 v33, vcc, v24, v28, v24
	v_mul_f32_e32 v36, v33, v32
	v_fma_f32 v37, -v25, v36, v33
	v_fmac_f32_e32 v36, v37, v32
	v_fma_f32 v25, -v25, v36, v33
	v_div_fmas_f32 v25, v25, v32, v36
	v_div_fixup_f32 v28, v25, v28, v24
	v_pk_add_f32 v[24:25], v[26:27], v[50:51] op_sel:[0,1] neg_lo:[0,1] neg_hi:[0,1]
	s_nop 0
	v_pk_mul_f32 v[24:25], v[24:25], v[52:53] op_sel_hi:[1,0]
	s_nop 0
	v_pk_fma_f32 v[24:25], v[24:25], v[106:107], v[120:121]
	s_nop 0
	v_mul_f32_e32 v26, 0xbfb8aa3b, v24
	v_mul_f32_e32 v27, 0xbfb8aa3b, v25
	v_exp_f32_e32 v26, v26
	v_exp_f32_e32 v27, v27
	s_nop 0
	v_pk_add_f32 v[26:27], v[26:27], 1.0 op_sel_hi:[1,0]
	s_nop 0
	v_div_scale_f32 v32, s[0:1], v27, v27, v25
	v_rcp_f32_e32 v33, v32
	s_nop 0
	v_fma_f32 v34, -v32, v33, 1.0
	v_fmac_f32_e32 v33, v34, v33
	v_div_scale_f32 v34, vcc, v25, v27, v25
	v_mul_f32_e32 v35, v34, v33
	v_fma_f32 v36, -v32, v35, v34
	v_fmac_f32_e32 v35, v36, v33
	v_fma_f32 v32, -v32, v35, v34
	v_div_fmas_f32 v32, v32, v33, v35
	v_div_fixup_f32 v27, v32, v27, v25
	v_div_scale_f32 v25, s[0:1], v26, v26, v24
	v_rcp_f32_e32 v32, v25
	s_nop 0
	v_fma_f32 v33, -v25, v32, 1.0
	v_fmac_f32_e32 v32, v33, v32
	v_div_scale_f32 v33, vcc, v24, v26, v24
	v_mul_f32_e32 v34, v33, v32
	v_fma_f32 v35, -v25, v34, v33
	v_fmac_f32_e32 v34, v35, v32
	v_fma_f32 v25, -v25, v34, v33
	v_div_fmas_f32 v25, v25, v32, v34
	v_div_fixup_f32 v32, v25, v26, v24
	v_cvt_pk_bf16_f32 v24, v40, v41
	v_cvt_pk_bf16_f32 v25, v30, v31
	v_cvt_pk_bf16_f32 v26, v28, v29
	v_cvt_pk_bf16_f32 v27, v32, v27
	global_store_dwordx4 v[48:49], v[24:27], off
	s_nop 0
	v_pk_fma_f32 v[16:17], v[16:17], v[126:127], v[138:139]
	v_pk_fma_f32 v[20:21], v[20:21], v[134:135], v[142:143]
	s_nop 0
	v_mul_f32_e32 v32, 0xbfb8aa3b, v20
	v_mul_f32_e32 v33, 0xbfb8aa3b, v21
	v_exp_f32_e32 v32, v32
	v_exp_f32_e32 v33, v33
	s_nop 0
	v_pk_add_f32 v[32:33], v[32:33], 1.0 op_sel_hi:[1,0]
	s_nop 0
	v_div_scale_f32 v36, s[0:1], v33, v33, v21
	v_rcp_f32_e32 v37, v36
	s_nop 0
	v_fma_f32 v40, -v36, v37, 1.0
	v_fmac_f32_e32 v37, v40, v37
	v_div_scale_f32 v40, vcc, v21, v33, v21
	v_mul_f32_e32 v41, v40, v37
	v_fma_f32 v42, -v36, v41, v40
	v_fmac_f32_e32 v41, v42, v37
	v_fma_f32 v36, -v36, v41, v40
	v_div_fmas_f32 v36, v36, v37, v41
	v_div_fixup_f32 v33, v36, v33, v21
	v_div_scale_f32 v21, s[0:1], v32, v32, v20
	v_rcp_f32_e32 v36, v21
	s_nop 0
	v_fma_f32 v37, -v21, v36, 1.0
	v_fmac_f32_e32 v36, v37, v36
	v_div_scale_f32 v37, vcc, v20, v32, v20
	v_mul_f32_e32 v40, v37, v36
	v_fma_f32 v41, -v21, v40, v37
	v_fmac_f32_e32 v40, v41, v36
	v_fma_f32 v21, -v21, v40, v37
	v_div_fmas_f32 v21, v21, v36, v40
	v_div_fixup_f32 v32, v21, v32, v20
	v_pk_add_f32 v[20:21], v[22:23], v[50:51] op_sel:[0,1] neg_lo:[0,1] neg_hi:[0,1]
	s_nop 0
	v_pk_mul_f32 v[20:21], v[20:21], v[52:53] op_sel_hi:[1,0]
	s_nop 0
	v_pk_fma_f32 v[20:21], v[20:21], v[136:137], v[144:145]
	s_nop 0
	v_mul_f32_e32 v22, 0xbfb8aa3b, v20
	v_mul_f32_e32 v23, 0xbfb8aa3b, v21
	v_exp_f32_e32 v22, v22
	v_exp_f32_e32 v23, v23
	s_nop 0
	v_pk_add_f32 v[22:23], v[22:23], 1.0 op_sel_hi:[1,0]
	s_nop 0
	v_div_scale_f32 v34, s[0:1], v23, v23, v21
	v_rcp_f32_e32 v35, v34
	s_nop 0
	v_fma_f32 v36, -v34, v35, 1.0
	v_fmac_f32_e32 v35, v36, v35
	v_div_scale_f32 v36, vcc, v21, v23, v21
	v_mul_f32_e32 v37, v36, v35
	v_fma_f32 v38, -v34, v37, v36
	v_fmac_f32_e32 v37, v38, v35
	v_fma_f32 v34, -v34, v37, v36
	v_div_fmas_f32 v34, v34, v35, v37
	v_div_fixup_f32 v23, v34, v23, v21
	v_div_scale_f32 v21, s[0:1], v22, v22, v20
	v_rcp_f32_e32 v34, v21
	s_nop 0
	v_fma_f32 v35, -v21, v34, 1.0
	v_fmac_f32_e32 v34, v35, v34
	v_div_scale_f32 v35, vcc, v20, v22, v20
	v_mul_f32_e32 v36, v35, v34
	v_fma_f32 v37, -v21, v36, v35
	v_fmac_f32_e32 v36, v37, v34
	v_fma_f32 v21, -v21, v36, v35
	v_div_fmas_f32 v21, v21, v34, v36
	v_div_fixup_f32 v22, v21, v22, v20
	v_mul_f32_e32 v20, 0xbfb8aa3b, v16
	v_mul_f32_e32 v21, 0xbfb8aa3b, v17
	v_exp_f32_e32 v20, v20
	v_exp_f32_e32 v21, v21
	s_nop 0
	v_pk_add_f32 v[20:21], v[20:21], 1.0 op_sel_hi:[1,0]
	s_nop 0
	v_div_scale_f32 v24, s[0:1], v21, v21, v17
	v_rcp_f32_e32 v25, v24
	s_nop 0
	v_fma_f32 v28, -v24, v25, 1.0
	v_fmac_f32_e32 v25, v28, v25
	v_div_scale_f32 v28, vcc, v17, v21, v17
	v_mul_f32_e32 v29, v28, v25
	v_fma_f32 v34, -v24, v29, v28
	v_fmac_f32_e32 v29, v34, v25
	v_fma_f32 v24, -v24, v29, v28
	v_div_fmas_f32 v24, v24, v25, v29
	v_div_fixup_f32 v21, v24, v21, v17
	v_div_scale_f32 v17, s[0:1], v20, v20, v16
	v_rcp_f32_e32 v24, v17
	s_nop 0
	v_fma_f32 v25, -v17, v24, 1.0
	v_fmac_f32_e32 v24, v25, v24
	v_div_scale_f32 v25, vcc, v16, v20, v16
	v_mul_f32_e32 v28, v25, v24
	v_fma_f32 v29, -v17, v28, v25
	v_fmac_f32_e32 v28, v29, v24
	v_fma_f32 v17, -v17, v28, v25
	v_div_fmas_f32 v17, v17, v24, v28
	v_div_fixup_f32 v20, v17, v20, v16
	v_pk_add_f32 v[16:17], v[18:19], v[50:51] op_sel:[0,1] neg_lo:[0,1] neg_hi:[0,1]
	s_nop 0
	v_pk_mul_f32 v[16:17], v[16:17], v[52:53] op_sel_hi:[1,0]
	s_nop 0
	v_pk_fma_f32 v[16:17], v[16:17], v[128:129], v[140:141]
	s_nop 0
	v_mul_f32_e32 v18, 0xbfb8aa3b, v16
	v_mul_f32_e32 v19, 0xbfb8aa3b, v17
	v_exp_f32_e32 v18, v18
	v_exp_f32_e32 v19, v19
	s_nop 0
	v_pk_add_f32 v[18:19], v[18:19], 1.0 op_sel_hi:[1,0]
	s_nop 0
	v_div_scale_f32 v24, s[0:1], v19, v19, v17
	v_rcp_f32_e32 v25, v24
	s_nop 0
	v_fma_f32 v26, -v24, v25, 1.0
	v_fmac_f32_e32 v25, v26, v25
	v_div_scale_f32 v26, vcc, v17, v19, v17
	v_mul_f32_e32 v27, v26, v25
	v_fma_f32 v28, -v24, v27, v26
	v_fmac_f32_e32 v27, v28, v25
	v_fma_f32 v24, -v24, v27, v26
	v_div_fmas_f32 v24, v24, v25, v27
	v_div_fixup_f32 v19, v24, v19, v17
	v_div_scale_f32 v17, s[0:1], v18, v18, v16
	v_rcp_f32_e32 v24, v17
	s_nop 0
	v_fma_f32 v25, -v17, v24, 1.0
	v_fmac_f32_e32 v24, v25, v24
	v_div_scale_f32 v25, vcc, v16, v18, v16
	v_mul_f32_e32 v26, v25, v24
	v_fma_f32 v27, -v17, v26, v25
	v_fmac_f32_e32 v26, v27, v24
	v_fma_f32 v17, -v17, v26, v25
	v_div_fmas_f32 v17, v17, v24, v26
	v_div_fixup_f32 v24, v17, v18, v16
	v_cvt_pk_bf16_f32 v16, v32, v33
	v_cvt_pk_bf16_f32 v17, v22, v23
	v_cvt_pk_bf16_f32 v18, v20, v21
	v_cvt_pk_bf16_f32 v19, v24, v19
	global_store_dwordx4 v[48:49], v[16:19], off offset:16
	s_nop 0
	v_pk_fma_f32 v[8:9], v[8:9], v[146:147], v[154:155]
	v_pk_fma_f32 v[12:13], v[12:13], v[150:151], v[160:161]
	s_nop 0
	v_mul_f32_e32 v24, 0xbfb8aa3b, v12
	v_mul_f32_e32 v25, 0xbfb8aa3b, v13
	v_exp_f32_e32 v24, v24
	v_exp_f32_e32 v25, v25
	s_nop 0
	v_pk_add_f32 v[24:25], v[24:25], 1.0 op_sel_hi:[1,0]
	s_nop 0
	v_div_scale_f32 v28, s[0:1], v25, v25, v13
	v_rcp_f32_e32 v29, v28
	s_nop 0
	v_fma_f32 v32, -v28, v29, 1.0
	v_fmac_f32_e32 v29, v32, v29
	v_div_scale_f32 v32, vcc, v13, v25, v13
	v_mul_f32_e32 v33, v32, v29
	v_fma_f32 v34, -v28, v33, v32
	v_fmac_f32_e32 v33, v34, v29
	v_fma_f32 v28, -v28, v33, v32
	v_div_fmas_f32 v28, v28, v29, v33
	v_div_fixup_f32 v25, v28, v25, v13
	v_div_scale_f32 v13, s[0:1], v24, v24, v12
	v_rcp_f32_e32 v28, v13
	s_nop 0
	v_fma_f32 v29, -v13, v28, 1.0
	v_fmac_f32_e32 v28, v29, v28
	v_div_scale_f32 v29, vcc, v12, v24, v12
	v_mul_f32_e32 v32, v29, v28
	v_fma_f32 v33, -v13, v32, v29
	v_fmac_f32_e32 v32, v33, v28
	v_fma_f32 v13, -v13, v32, v29
	v_div_fmas_f32 v13, v13, v28, v32
	v_div_fixup_f32 v24, v13, v24, v12
	v_pk_add_f32 v[12:13], v[14:15], v[50:51] op_sel:[0,1] neg_lo:[0,1] neg_hi:[0,1]
	s_nop 0
	v_pk_mul_f32 v[12:13], v[12:13], v[52:53] op_sel_hi:[1,0]
	s_nop 0
	v_pk_fma_f32 v[12:13], v[12:13], v[152:153], v[162:163]
	s_nop 0
	v_mul_f32_e32 v14, 0xbfb8aa3b, v12
	v_mul_f32_e32 v15, 0xbfb8aa3b, v13
	v_exp_f32_e32 v14, v14
	v_exp_f32_e32 v15, v15
	s_nop 0
	v_pk_add_f32 v[14:15], v[14:15], 1.0 op_sel_hi:[1,0]
	s_nop 0
	v_div_scale_f32 v26, s[0:1], v15, v15, v13
	v_rcp_f32_e32 v27, v26
	s_nop 0
	v_fma_f32 v28, -v26, v27, 1.0
	v_fmac_f32_e32 v27, v28, v27
	v_div_scale_f32 v28, vcc, v13, v15, v13
	v_mul_f32_e32 v29, v28, v27
	v_fma_f32 v30, -v26, v29, v28
	v_fmac_f32_e32 v29, v30, v27
	v_fma_f32 v26, -v26, v29, v28
	v_div_fmas_f32 v26, v26, v27, v29
	v_div_fixup_f32 v15, v26, v15, v13
	v_div_scale_f32 v13, s[0:1], v14, v14, v12
	v_rcp_f32_e32 v26, v13
	s_nop 0
	v_fma_f32 v27, -v13, v26, 1.0
	v_fmac_f32_e32 v26, v27, v26
	v_div_scale_f32 v27, vcc, v12, v14, v12
	v_mul_f32_e32 v28, v27, v26
	v_fma_f32 v29, -v13, v28, v27
	v_fmac_f32_e32 v28, v29, v26
	v_fma_f32 v13, -v13, v28, v27
	v_div_fmas_f32 v13, v13, v26, v28
	v_div_fixup_f32 v14, v13, v14, v12
	v_mul_f32_e32 v12, 0xbfb8aa3b, v8
	v_mul_f32_e32 v13, 0xbfb8aa3b, v9
	v_exp_f32_e32 v12, v12
	v_exp_f32_e32 v13, v13
	s_nop 0
	v_pk_add_f32 v[12:13], v[12:13], 1.0 op_sel_hi:[1,0]
	s_nop 0
	v_div_scale_f32 v16, s[0:1], v13, v13, v9
	v_rcp_f32_e32 v17, v16
	s_nop 0
	v_fma_f32 v20, -v16, v17, 1.0
	v_fmac_f32_e32 v17, v20, v17
	v_div_scale_f32 v20, vcc, v9, v13, v9
	v_mul_f32_e32 v21, v20, v17
	v_fma_f32 v26, -v16, v21, v20
	v_fmac_f32_e32 v21, v26, v17
	v_fma_f32 v16, -v16, v21, v20
	v_div_fmas_f32 v16, v16, v17, v21
	v_div_fixup_f32 v13, v16, v13, v9
	v_div_scale_f32 v9, s[0:1], v12, v12, v8
	v_rcp_f32_e32 v16, v9
	s_nop 0
	v_fma_f32 v17, -v9, v16, 1.0
	v_fmac_f32_e32 v16, v17, v16
	v_div_scale_f32 v17, vcc, v8, v12, v8
	v_mul_f32_e32 v20, v17, v16
	v_fma_f32 v21, -v9, v20, v17
	v_fmac_f32_e32 v20, v21, v16
	v_fma_f32 v9, -v9, v20, v17
	v_div_fmas_f32 v9, v9, v16, v20
	v_div_fixup_f32 v12, v9, v12, v8
	v_pk_add_f32 v[8:9], v[10:11], v[50:51] op_sel:[0,1] neg_lo:[0,1] neg_hi:[0,1]
	s_nop 0
	v_pk_mul_f32 v[8:9], v[8:9], v[52:53] op_sel_hi:[1,0]
	s_nop 0
	v_pk_fma_f32 v[8:9], v[8:9], v[148:149], v[156:157]
	s_nop 0
	v_mul_f32_e32 v10, 0xbfb8aa3b, v8
	v_mul_f32_e32 v11, 0xbfb8aa3b, v9
	v_exp_f32_e32 v10, v10
	v_exp_f32_e32 v11, v11
	s_nop 0
	v_pk_add_f32 v[10:11], v[10:11], 1.0 op_sel_hi:[1,0]
	s_nop 0
	v_div_scale_f32 v16, s[0:1], v11, v11, v9
	v_rcp_f32_e32 v17, v16
	s_nop 0
	v_fma_f32 v18, -v16, v17, 1.0
	v_fmac_f32_e32 v17, v18, v17
	v_div_scale_f32 v18, vcc, v9, v11, v9
	v_mul_f32_e32 v19, v18, v17
	v_fma_f32 v20, -v16, v19, v18
	v_fmac_f32_e32 v19, v20, v17
	v_fma_f32 v16, -v16, v19, v18
	v_div_fmas_f32 v16, v16, v17, v19
	v_div_fixup_f32 v11, v16, v11, v9
	v_div_scale_f32 v9, s[0:1], v10, v10, v8
	v_rcp_f32_e32 v16, v9
	s_nop 0
	v_fma_f32 v17, -v9, v16, 1.0
	v_fmac_f32_e32 v16, v17, v16
	v_div_scale_f32 v17, vcc, v8, v10, v8
	v_mul_f32_e32 v18, v17, v16
	v_fma_f32 v19, -v9, v18, v17
	v_fmac_f32_e32 v18, v19, v16
	v_fma_f32 v9, -v9, v18, v17
	v_div_fmas_f32 v9, v9, v16, v18
	v_div_fixup_f32 v16, v9, v10, v8
	v_cvt_pk_bf16_f32 v8, v24, v25
	v_cvt_pk_bf16_f32 v9, v14, v15
	v_cvt_pk_bf16_f32 v10, v12, v13
	v_cvt_pk_bf16_f32 v11, v16, v11
	global_store_dwordx4 v[48:49], v[8:11], off offset:32
	s_nop 0
	v_pk_fma_f32 v[0:1], v[0:1], v[168:169], v[176:177]
	v_pk_fma_f32 v[4:5], v[4:5], v[172:173], v[184:185]
	s_nop 0
	v_mul_f32_e32 v16, 0xbfb8aa3b, v4
	v_mul_f32_e32 v17, 0xbfb8aa3b, v5
	v_exp_f32_e32 v16, v16
	v_exp_f32_e32 v17, v17
	s_nop 0
	v_pk_add_f32 v[16:17], v[16:17], 1.0 op_sel_hi:[1,0]
	s_nop 0
	v_div_scale_f32 v20, s[0:1], v17, v17, v5
	v_rcp_f32_e32 v21, v20
	s_nop 0
	v_fma_f32 v24, -v20, v21, 1.0
	v_fmac_f32_e32 v21, v24, v21
	v_div_scale_f32 v24, vcc, v5, v17, v5
	v_mul_f32_e32 v25, v24, v21
	v_fma_f32 v26, -v20, v25, v24
	v_fmac_f32_e32 v25, v26, v21
	v_fma_f32 v20, -v20, v25, v24
	v_div_fmas_f32 v20, v20, v21, v25
	v_div_fixup_f32 v17, v20, v17, v5
	v_div_scale_f32 v5, s[0:1], v16, v16, v4
	v_rcp_f32_e32 v20, v5
	s_nop 0
	v_fma_f32 v21, -v5, v20, 1.0
	v_fmac_f32_e32 v20, v21, v20
	v_div_scale_f32 v21, vcc, v4, v16, v4
	v_mul_f32_e32 v24, v21, v20
	v_fma_f32 v25, -v5, v24, v21
	v_fmac_f32_e32 v24, v25, v20
	v_fma_f32 v5, -v5, v24, v21
	v_div_fmas_f32 v5, v5, v20, v24
	v_div_fixup_f32 v16, v5, v16, v4
	v_pk_add_f32 v[4:5], v[6:7], v[50:51] op_sel:[0,1] neg_lo:[0,1] neg_hi:[0,1]
	s_nop 0
	v_pk_mul_f32 v[4:5], v[4:5], v[52:53] op_sel_hi:[1,0]
	s_nop 0
	v_pk_fma_f32 v[4:5], v[4:5], v[174:175], v[186:187]
	s_nop 0
	v_mul_f32_e32 v6, 0xbfb8aa3b, v4
	v_mul_f32_e32 v7, 0xbfb8aa3b, v5
	v_exp_f32_e32 v6, v6
	v_exp_f32_e32 v7, v7
	s_nop 0
	v_pk_add_f32 v[6:7], v[6:7], 1.0 op_sel_hi:[1,0]
	s_nop 0
	v_div_scale_f32 v18, s[0:1], v7, v7, v5
	v_rcp_f32_e32 v19, v18
	s_nop 0
	v_fma_f32 v20, -v18, v19, 1.0
	v_fmac_f32_e32 v19, v20, v19
	v_div_scale_f32 v20, vcc, v5, v7, v5
	v_mul_f32_e32 v21, v20, v19
	v_fma_f32 v22, -v18, v21, v20
	v_fmac_f32_e32 v21, v22, v19
	v_fma_f32 v18, -v18, v21, v20
	v_div_fmas_f32 v18, v18, v19, v21
	v_div_fixup_f32 v7, v18, v7, v5
	v_div_scale_f32 v5, s[0:1], v6, v6, v4
	v_rcp_f32_e32 v18, v5
	s_nop 0
	v_fma_f32 v19, -v5, v18, 1.0
	v_fmac_f32_e32 v18, v19, v18
	v_div_scale_f32 v19, vcc, v4, v6, v4
	v_mul_f32_e32 v20, v19, v18
	v_fma_f32 v21, -v5, v20, v19
	v_fmac_f32_e32 v20, v21, v18
	v_fma_f32 v5, -v5, v20, v19
	v_div_fmas_f32 v5, v5, v18, v20
	v_div_fixup_f32 v6, v5, v6, v4
	v_mul_f32_e32 v4, 0xbfb8aa3b, v0
	v_mul_f32_e32 v5, 0xbfb8aa3b, v1
	v_exp_f32_e32 v4, v4
	v_exp_f32_e32 v5, v5
	s_nop 0
	v_pk_add_f32 v[4:5], v[4:5], 1.0 op_sel_hi:[1,0]
	s_nop 0
	v_div_scale_f32 v8, s[0:1], v5, v5, v1
	v_rcp_f32_e32 v9, v8
	s_nop 0
	v_fma_f32 v12, -v8, v9, 1.0
	v_fmac_f32_e32 v9, v12, v9
	v_div_scale_f32 v12, vcc, v1, v5, v1
	v_mul_f32_e32 v13, v12, v9
	v_fma_f32 v18, -v8, v13, v12
	v_fmac_f32_e32 v13, v18, v9
	v_fma_f32 v8, -v8, v13, v12
	v_div_fmas_f32 v8, v8, v9, v13
	v_div_fixup_f32 v5, v8, v5, v1
	v_div_scale_f32 v1, s[0:1], v4, v4, v0
	v_rcp_f32_e32 v8, v1
	s_nop 0
	v_fma_f32 v9, -v1, v8, 1.0
	v_fmac_f32_e32 v8, v9, v8
	v_div_scale_f32 v9, vcc, v0, v4, v0
	v_mul_f32_e32 v12, v9, v8
	v_fma_f32 v13, -v1, v12, v9
	v_fmac_f32_e32 v12, v13, v8
	v_fma_f32 v1, -v1, v12, v9
	v_div_fmas_f32 v1, v1, v8, v12
	v_div_fixup_f32 v4, v1, v4, v0
	v_pk_add_f32 v[0:1], v[2:3], v[50:51] op_sel:[0,1] neg_lo:[0,1] neg_hi:[0,1]
	s_nop 0
	v_pk_mul_f32 v[0:1], v[0:1], v[52:53] op_sel_hi:[1,0]
	s_nop 0
	v_pk_fma_f32 v[0:1], v[0:1], v[170:171], v[178:179]
	s_nop 0
	v_mul_f32_e32 v2, 0xbfb8aa3b, v0
	v_mul_f32_e32 v3, 0xbfb8aa3b, v1
	v_exp_f32_e32 v2, v2
	v_exp_f32_e32 v3, v3
	s_nop 0
	v_pk_add_f32 v[2:3], v[2:3], 1.0 op_sel_hi:[1,0]
	s_nop 0
	v_div_scale_f32 v8, s[0:1], v3, v3, v1
	v_rcp_f32_e32 v9, v8
	s_nop 0
	v_fma_f32 v10, -v8, v9, 1.0
	v_fmac_f32_e32 v9, v10, v9
	v_div_scale_f32 v10, vcc, v1, v3, v1
	v_mul_f32_e32 v11, v10, v9
	v_fma_f32 v12, -v8, v11, v10
	v_fmac_f32_e32 v11, v12, v9
	v_fma_f32 v8, -v8, v11, v10
	v_div_fmas_f32 v8, v8, v9, v11
	v_div_fixup_f32 v3, v8, v3, v1
	v_div_scale_f32 v1, s[0:1], v2, v2, v0
	v_rcp_f32_e32 v8, v1
	s_nop 0
	v_fma_f32 v9, -v1, v8, 1.0
	v_fmac_f32_e32 v8, v9, v8
	v_div_scale_f32 v9, vcc, v0, v2, v0
	v_mul_f32_e32 v10, v9, v8
	v_fma_f32 v11, -v1, v10, v9
	v_fmac_f32_e32 v10, v11, v8
	v_fma_f32 v1, -v1, v10, v9
	v_div_fmas_f32 v1, v1, v8, v10
	v_div_fixup_f32 v8, v1, v2, v0
	v_cvt_pk_bf16_f32 v0, v16, v17
	v_cvt_pk_bf16_f32 v1, v6, v7
	v_cvt_pk_bf16_f32 v2, v4, v5
	v_cvt_pk_bf16_f32 v3, v8, v3
	global_store_dwordx4 v[48:49], v[0:3], off offset:48
	s_barrier
	s_cbranch_scc0 .LBB0_858
